# no-permlane P/V key order (stale hazard pads removed) + MLA loops: deferred row-sum lane exchange, scalar-base DMA addresses
# speedup vs baseline: 1.0052x; 1.0052x over previous
.LBB0_892:
	v_sub_co_u32_e64 v66, s[28:29], s4, 3
	s_and_b32 s21, s4, 1
	s_add_i32 s1, s4, 1
	v_readfirstlane_b32 s4, v66
	s_lshl_b64 s[36:37], s[4:5], 6
	s_and_b64 s[38:39], s[28:29], exec
	s_cselect_b32 s37, s15, s37
	s_cselect_b32 s36, s14, s36
	s_mul_i32 s39, s37, 0xc00
	s_mul_hi_u32 s40, s36, 0xc00
	s_cselect_b32 s4, s13, s23
	s_cselect_b32 s38, s12, s22
	s_add_i32 s40, s40, s39
	s_mul_i32 s39, s36, 0xc00
	s_add_u32 s38, s38, s39
	s_addc_u32 s39, s4, s40
	s_xor_b32 s4, s21, 1
	s_mulk_i32 s4, 0x6000
	s_add_i32 s4, s69, s4
	s_add_i32 m0, s4, 0x8000
	s_nop 0
	global_load_lds_dwordx4 v222, s[38:39]
	s_add_i32 m0, s4, 0xa000
	s_lshl_b64 s[36:37], s[36:37], 12
	global_load_lds_dwordx4 v223, s[38:39]
	s_add_i32 m0, s4, 0xc000
	s_and_b64 s[28:29], s[28:29], exec
	s_cselect_b32 s28, s24, s33
	s_cselect_b32 s4, s25, s35
	s_add_u32 s28, s28, s36
	s_addc_u32 s29, s4, s37
	s_lshl_b32 s4, s21, 14
	s_xor_b32 s36, s4, 0x4000
	s_add_i32 s36, s69, s36
	global_load_lds_dwordx4 v224, s[38:39]
	s_mov_b32 m0, s36
	s_mulk_i32 s21, 0x6000
	global_load_lds_dwordx4 v225, s[28:29]
	s_add_i32 m0, s36, 0x2000
	s_nop 0
	global_load_lds_dwordx4 v226, s[28:29]
	v_add_u32_e32 v70, s21, v179
	v_add_u32_e32 v71, v70, v178
	ds_read_b128 v[66:69], v71 offset:32768
	v_add_u32_e32 v153, v70, v180
	v_add_u32_e32 v155, v70, v181
	v_add_u32_e32 v157, v70, v182
	v_add_u32_e32 v159, v70, v183
	v_add_u32_e32 v193, v70, v184
	v_add_u32_e32 v198, v70, v185
	v_add_u32_e32 v199, v70, v186
	v_add_u32_e32 v200, v70, v187
	s_waitcnt lgkmcnt(0)
	v_mfma_f32_32x32x16_bf16 v[82:97], v[66:69], v[142:145], 0
	ds_read_b128 v[66:69], v153 offset:32768
	v_add_u32_e32 v201, v70, v188
	v_add_u32_e32 v202, v70, v189
	v_add_u32_e32 v203, v70, v190
	s_waitcnt lgkmcnt(0)
	v_mfma_f32_32x32x16_bf16 v[82:97], v[66:69], v[138:141], v[82:97]
	ds_read_b128 v[66:69], v155 offset:32768
	s_waitcnt lgkmcnt(0)
	v_mfma_f32_32x32x16_bf16 v[82:97], v[66:69], v[134:137], v[82:97]
	ds_read_b128 v[66:69], v157 offset:32768
	s_waitcnt lgkmcnt(0)
	v_mfma_f32_32x32x16_bf16 v[82:97], v[66:69], v[130:133], v[82:97]
	ds_read_b128 v[66:69], v159 offset:32768
	s_waitcnt lgkmcnt(0)
	v_mfma_f32_32x32x16_bf16 v[82:97], v[66:69], v[126:129], v[82:97]
	ds_read_b128 v[66:69], v193 offset:32768
	s_waitcnt lgkmcnt(0)
	v_mfma_f32_32x32x16_bf16 v[82:97], v[66:69], v[122:125], v[82:97]
	ds_read_b128 v[66:69], v198 offset:32768
	s_waitcnt lgkmcnt(0)
	v_mfma_f32_32x32x16_bf16 v[82:97], v[66:69], v[118:121], v[82:97]
	ds_read_b128 v[66:69], v199 offset:32768
	s_waitcnt lgkmcnt(0)
	v_mfma_f32_32x32x16_bf16 v[82:97], v[66:69], v[114:117], v[82:97]
	ds_read_b128 v[66:69], v200 offset:32768
	s_waitcnt lgkmcnt(0)
	v_mfma_f32_32x32x16_bf16 v[82:97], v[66:69], v[110:113], v[82:97]
	ds_read_b128 v[66:69], v201 offset:32768
	s_waitcnt lgkmcnt(0)
	v_mfma_f32_32x32x16_bf16 v[82:97], v[66:69], v[106:109], v[82:97]
	ds_read_b128 v[66:69], v202 offset:32768
	s_waitcnt lgkmcnt(0)
	v_mfma_f32_32x32x16_bf16 v[82:97], v[66:69], v[102:105], v[82:97]
	ds_read_b128 v[66:69], v203 offset:32768
	s_waitcnt lgkmcnt(0)
	v_mfma_f32_32x32x16_bf16 v[82:97], v[66:69], v[98:101], v[82:97]
	ds_read_b128 v[66:69], v71 offset:45056
	ds_read_b128 v[194:197], v153 offset:45056
	s_nop 9
	v_exp_f32_e32 v204, v88
	v_exp_f32_e32 v205, v89
	v_exp_f32_e32 v206, v90
	v_exp_f32_e32 v207, v91
	v_exp_f32_e32 v208, v92
	v_exp_f32_e32 v209, v93
	v_exp_f32_e32 v210, v94
	s_waitcnt lgkmcnt(0)
	v_mfma_f32_32x32x16_bf16 v[66:81], v[66:69], v[142:145], 0
	v_exp_f32_e32 v211, v95
	v_exp_f32_e32 v212, v96
	v_exp_f32_e32 v213, v97
	v_add_u32_e32 v153, s4, v176
	v_cvt_pk_bf16_f32 v88, v210, v211
	v_cvt_pk_bf16_f32 v89, v212, v213
	v_mfma_f32_32x32x16_bf16 v[66:81], v[194:197], v[138:141], v[66:81]
	ds_read_b128 v[194:197], v155 offset:45056
	v_exp_f32_e32 v155, v82
	s_waitcnt lgkmcnt(0)
	v_mfma_f32_32x32x16_bf16 v[66:81], v[194:197], v[134:137], v[66:81]
	ds_read_b128 v[194:197], v157 offset:45056
	v_exp_f32_e32 v157, v83
	s_nop 0
	v_cvt_pk_bf16_f32 v82, v155, v157
	s_waitcnt lgkmcnt(0)
	v_mfma_f32_32x32x16_bf16 v[66:81], v[194:197], v[130:133], v[66:81]
	ds_read_b128 v[194:197], v159 offset:45056
	v_exp_f32_e32 v159, v84
	s_waitcnt lgkmcnt(0)
	v_mfma_f32_32x32x16_bf16 v[66:81], v[194:197], v[126:129], v[66:81]
	ds_read_b128 v[194:197], v193 offset:45056
	v_exp_f32_e32 v193, v85
	v_cvt_pk_bf16_f32 v85, v204, v205
	v_cvt_pk_bf16_f32 v83, v159, v193
	s_waitcnt lgkmcnt(0)
	v_mfma_f32_32x32x16_bf16 v[66:81], v[194:197], v[122:125], v[66:81]
	ds_read_b128 v[194:197], v198 offset:45056
	s_waitcnt lgkmcnt(0)
	v_mfma_f32_32x32x16_bf16 v[66:81], v[194:197], v[118:121], v[66:81]
	ds_read_b128 v[194:197], v199 offset:45056
	s_waitcnt lgkmcnt(0)
	v_mfma_f32_32x32x16_bf16 v[66:81], v[194:197], v[114:117], v[66:81]
	ds_read_b128 v[194:197], v200 offset:45056
	s_waitcnt lgkmcnt(0)
	v_mfma_f32_32x32x16_bf16 v[66:81], v[194:197], v[110:113], v[66:81]
	ds_read_b128 v[194:197], v201 offset:45056
	s_waitcnt lgkmcnt(0)
	v_mfma_f32_32x32x16_bf16 v[66:81], v[194:197], v[106:109], v[66:81]
	ds_read_b128 v[194:197], v202 offset:45056
	v_exp_f32_e32 v202, v86
	v_cvt_pk_bf16_f32 v86, v206, v207
	s_waitcnt lgkmcnt(0)
	v_mfma_f32_32x32x16_bf16 v[66:81], v[194:197], v[102:105], v[66:81]
	ds_read_b128 v[194:197], v203 offset:45056
	v_exp_f32_e32 v203, v87
	v_cvt_pk_bf16_f32 v87, v208, v209
	v_cvt_pk_bf16_f32 v84, v202, v203
	s_waitcnt lgkmcnt(0)
	v_mfma_f32_32x32x16_bf16 v[66:81], v[194:197], v[98:101], v[66:81]
	ds_read_b64_tr_b16 v[90:91], v153 offset:0
	ds_read_b64_tr_b16 v[92:93], v153 offset:0x800
	ds_read_b64_tr_b16 v[94:95], v153 offset:0x1000
	ds_read_b64_tr_b16 v[96:97], v153 offset:0x1800
	ds_read_b64_tr_b16 v[194:195], v153 offset:0x200
	ds_read_b64_tr_b16 v[196:197], v153 offset:0xa00
	ds_read_b64_tr_b16 v[198:199], v153 offset:0x1200
	ds_read_b64_tr_b16 v[200:201], v153 offset:0x1a00
	s_waitcnt lgkmcnt(4)
	s_nop 0
	v_mfma_f32_32x32x16_bf16 v[2:17], v[82:85], v[90:93], v[2:17]
	s_nop 9
	v_exp_f32_e32 v214, v66
	v_exp_f32_e32 v215, v67
	v_exp_f32_e32 v216, v68
	v_exp_f32_e32 v217, v69
	v_mfma_f32_32x32x16_bf16 v[2:17], v[86:89], v[94:97], v[2:17]
	ds_read_b64_tr_b16 v[66:67], v153 offset:0x400
	ds_read_b64_tr_b16 v[68:69], v153 offset:0xc00
	ds_read_b64_tr_b16 v[90:91], v153 offset:0x1400
	ds_read_b64_tr_b16 v[92:93], v153 offset:0x1c00
	s_waitcnt lgkmcnt(4)
	v_mfma_f32_32x32x16_bf16 v[18:33], v[82:85], v[194:197], v[18:33]
	v_exp_f32_e32 v194, v70
	v_exp_f32_e32 v195, v71
	v_exp_f32_e32 v196, v72
	v_exp_f32_e32 v197, v73
	v_mfma_f32_32x32x16_bf16 v[18:33], v[86:89], v[198:201], v[18:33]
	ds_read_b64_tr_b16 v[70:71], v153 offset:0x600
	ds_read_b64_tr_b16 v[72:73], v153 offset:0xe00
	ds_read_b64_tr_b16 v[94:95], v153 offset:0x1600
	ds_read_b64_tr_b16 v[96:97], v153 offset:0x1e00
	s_waitcnt lgkmcnt(4)
	v_mfma_f32_32x32x16_bf16 v[34:49], v[82:85], v[66:69], v[34:49]
	v_exp_f32_e32 v198, v74
	v_exp_f32_e32 v199, v75
	v_exp_f32_e32 v200, v76
	v_exp_f32_e32 v201, v77
	v_mfma_f32_32x32x16_bf16 v[34:49], v[86:89], v[90:93], v[34:49]
	ds_read_b64_tr_b16 v[66:67], v153 offset:0x2000
	ds_read_b64_tr_b16 v[68:69], v153 offset:0x2800
	ds_read_b64_tr_b16 v[74:75], v153 offset:0x3000
	ds_read_b64_tr_b16 v[76:77], v153 offset:0x3800
	s_waitcnt lgkmcnt(4)
	v_mfma_f32_32x32x16_bf16 v[50:65], v[82:85], v[70:73], v[50:65]
	v_exp_f32_e32 v249, v78
	v_exp_f32_e32 v250, v79
	v_cvt_pk_bf16_f32 v72, v194, v195
	v_cvt_pk_bf16_f32 v73, v196, v197
	v_mfma_f32_32x32x16_bf16 v[50:65], v[86:89], v[94:97], v[50:65]
	v_exp_f32_e32 v251, v80
	v_exp_f32_e32 v248, v81
	v_cvt_pk_bf16_f32 v78, v198, v199
	v_cvt_pk_bf16_f32 v79, v200, v201
	v_cvt_pk_bf16_f32 v80, v249, v250
	v_cvt_pk_bf16_f32 v70, v214, v215
	v_cvt_pk_bf16_f32 v71, v216, v217
	v_cvt_pk_bf16_f32 v81, v251, v248
	ds_read_b64_tr_b16 v[82:83], v153 offset:0x2200
	ds_read_b64_tr_b16 v[84:85], v153 offset:0x2a00
	ds_read_b64_tr_b16 v[86:87], v153 offset:0x3200
	ds_read_b64_tr_b16 v[88:89], v153 offset:0x3a00
	s_waitcnt lgkmcnt(4)
	s_nop 0
	v_mfma_f32_32x32x16_bf16 v[2:17], v[70:73], v[66:69], v[2:17]
	v_add_f32_e32 v246, v155, v157
	v_add_f32_e32 v247, v214, v215
	v_add_f32_e32 v246, v246, v159
	v_add_f32_e32 v247, v247, v216
	v_mfma_f32_32x32x16_bf16 v[2:17], v[78:81], v[74:77], v[2:17]
	v_add_f32_e32 v246, v246, v193
	v_add_f32_e32 v247, v247, v217
	v_add_f32_e32 v246, v246, v202
	v_add_f32_e32 v247, v247, v194
	ds_read_b64_tr_b16 v[66:67], v153 offset:0x2400
	ds_read_b64_tr_b16 v[68:69], v153 offset:0x2c00
	ds_read_b64_tr_b16 v[74:75], v153 offset:0x3400
	ds_read_b64_tr_b16 v[76:77], v153 offset:0x3c00
	s_waitcnt lgkmcnt(4)
	v_mfma_f32_32x32x16_bf16 v[18:33], v[70:73], v[82:85], v[18:33]
	v_add_f32_e32 v246, v246, v203
	v_add_f32_e32 v247, v247, v195
	v_add_f32_e32 v246, v246, v204
	v_add_f32_e32 v247, v247, v196
	v_mfma_f32_32x32x16_bf16 v[18:33], v[78:81], v[86:89], v[18:33]
	v_add_f32_e32 v246, v246, v205
	v_add_f32_e32 v247, v247, v197
	v_add_f32_e32 v246, v246, v206
	v_add_f32_e32 v247, v247, v198
	ds_read_b64_tr_b16 v[82:83], v153 offset:0x2600
	ds_read_b64_tr_b16 v[84:85], v153 offset:0x2e00
	ds_read_b64_tr_b16 v[86:87], v153 offset:0x3600
	ds_read_b64_tr_b16 v[88:89], v153 offset:0x3e00
	s_waitcnt lgkmcnt(4)
	v_mfma_f32_32x32x16_bf16 v[34:49], v[70:73], v[66:69], v[34:49]
	v_add_f32_e32 v246, v246, v207
	v_add_f32_e32 v247, v247, v199
	v_add_f32_e32 v246, v246, v208
	v_add_f32_e32 v247, v247, v200
	v_mfma_f32_32x32x16_bf16 v[34:49], v[78:81], v[74:77], v[34:49]
	v_add_f32_e32 v246, v246, v209
	v_add_f32_e32 v247, v247, v201
	v_add_f32_e32 v246, v246, v210
	v_add_f32_e32 v247, v247, v249
	s_waitcnt lgkmcnt(0)
	v_mfma_f32_32x32x16_bf16 v[50:65], v[70:73], v[82:85], v[50:65]
	v_add_f32_e32 v246, v246, v211
	v_add_f32_e32 v247, v247, v250
	v_add_f32_e32 v246, v246, v212
	v_add_f32_e32 v247, v247, v251
	v_add_f32_e32 v246, v246, v213
	v_add_f32_e32 v247, v247, v248
	v_add_f32_e32 v246, v246, v247
	v_add_f32_e32 v151, v151, v246
	s_waitcnt vmcnt(0)
	s_add_u32 s14, s14, 64
	s_addc_u32 s15, s15, 0
	s_cmp_eq_u32 s0, s1
	s_mov_b32 s4, s1
	s_waitcnt vmcnt(0)
	s_barrier
	v_mfma_f32_32x32x16_bf16 v[50:65], v[78:81], v[86:89], v[50:65]
	s_cbranch_scc0 .LBB0_892
	s_lshl_b32 s1, s68, 2
	s_add_i32 s4, s1, 0
	s_and_b32 s0, s0, 1
	s_add_i32 s4, s4, 0x1e000
	s_mul_i32 s1, s0, 0x6000
	v_add_u32_e32 v70, s1, v179
	v_add_u32_e32 v71, v70, v178
	ds_read_b128 v[66:69], v71 offset:32768
	v_add_u32_e32 v153, v70, v180
	v_add_u32_e32 v155, v70, v181
	v_add_u32_e32 v157, v70, v182
	v_add_u32_e32 v159, v70, v183
	v_add_u32_e32 v160, v70, v184
	v_add_u32_e32 v161, v70, v185
	v_add_u32_e32 v162, v70, v186
	v_add_u32_e32 v163, v70, v187
	s_waitcnt lgkmcnt(0)
	v_mfma_f32_32x32x16_bf16 v[82:97], v[66:69], v[142:145], 0
	ds_read_b128 v[66:69], v153 offset:32768
	v_add_u32_e32 v170, v70, v188
	v_add_u32_e32 v171, v70, v189
	v_add_u32_e32 v172, v70, v190
	s_waitcnt lgkmcnt(0)
	v_mfma_f32_32x32x16_bf16 v[82:97], v[66:69], v[138:141], v[82:97]
	ds_read_b128 v[66:69], v155 offset:32768
	s_waitcnt lgkmcnt(0)
	v_mfma_f32_32x32x16_bf16 v[82:97], v[66:69], v[134:137], v[82:97]
	ds_read_b128 v[66:69], v157 offset:32768
	s_waitcnt lgkmcnt(0)
	v_mfma_f32_32x32x16_bf16 v[82:97], v[66:69], v[130:133], v[82:97]
	ds_read_b128 v[66:69], v159 offset:32768
	s_waitcnt lgkmcnt(0)
	v_mfma_f32_32x32x16_bf16 v[82:97], v[66:69], v[126:129], v[82:97]
	ds_read_b128 v[66:69], v160 offset:32768
	s_waitcnt lgkmcnt(0)
	v_mfma_f32_32x32x16_bf16 v[82:97], v[66:69], v[122:125], v[82:97]
	ds_read_b128 v[66:69], v161 offset:32768
	s_waitcnt lgkmcnt(0)
	v_mfma_f32_32x32x16_bf16 v[82:97], v[66:69], v[118:121], v[82:97]
	ds_read_b128 v[66:69], v162 offset:32768
	s_waitcnt lgkmcnt(0)
	v_mfma_f32_32x32x16_bf16 v[82:97], v[66:69], v[114:117], v[82:97]
	ds_read_b128 v[66:69], v163 offset:32768
	s_waitcnt lgkmcnt(0)
	v_mfma_f32_32x32x16_bf16 v[82:97], v[66:69], v[110:113], v[82:97]
	ds_read_b128 v[66:69], v170 offset:32768
	s_waitcnt lgkmcnt(0)
	v_mfma_f32_32x32x16_bf16 v[82:97], v[66:69], v[106:109], v[82:97]
	ds_read_b128 v[66:69], v171 offset:32768
	s_waitcnt lgkmcnt(0)
	v_mfma_f32_32x32x16_bf16 v[82:97], v[66:69], v[102:105], v[82:97]
	ds_read_b128 v[66:69], v172 offset:32768
	s_waitcnt lgkmcnt(0)
	v_mfma_f32_32x32x16_bf16 v[82:97], v[66:69], v[98:101], v[82:97]
	ds_read_b128 v[66:69], v71 offset:45056
	s_waitcnt lgkmcnt(0)
	v_mfma_f32_32x32x16_bf16 v[66:81], v[66:69], v[142:145], 0
	ds_read_b128 v[142:145], v153 offset:45056
	s_waitcnt lgkmcnt(0)
	v_mfma_f32_32x32x16_bf16 v[66:81], v[142:145], v[138:141], v[66:81]
	ds_read_b128 v[138:141], v155 offset:45056
	s_waitcnt lgkmcnt(0)
	v_mfma_f32_32x32x16_bf16 v[66:81], v[138:141], v[134:137], v[66:81]
	ds_read_b128 v[134:137], v157 offset:45056
	s_waitcnt lgkmcnt(0)
	v_mfma_f32_32x32x16_bf16 v[66:81], v[134:137], v[130:133], v[66:81]
	ds_read_b128 v[130:133], v159 offset:45056
	s_waitcnt lgkmcnt(0)
	v_mfma_f32_32x32x16_bf16 v[66:81], v[130:133], v[126:129], v[66:81]
	ds_read_b128 v[126:129], v160 offset:45056
	s_waitcnt lgkmcnt(0)
	v_mfma_f32_32x32x16_bf16 v[66:81], v[126:129], v[122:125], v[66:81]
	ds_read_b128 v[122:125], v161 offset:45056
	s_waitcnt lgkmcnt(0)
	v_mfma_f32_32x32x16_bf16 v[66:81], v[122:125], v[118:121], v[66:81]
	ds_read_b128 v[118:121], v162 offset:45056
	v_exp_f32_e32 v122, v97
	s_waitcnt lgkmcnt(0)
	v_mfma_f32_32x32x16_bf16 v[66:81], v[118:121], v[114:117], v[66:81]
	ds_read_b128 v[114:117], v163 offset:45056
	v_exp_f32_e32 v118, v93
	v_exp_f32_e32 v119, v94
	v_exp_f32_e32 v120, v95
	v_exp_f32_e32 v121, v96
	s_waitcnt lgkmcnt(0)
	v_mfma_f32_32x32x16_bf16 v[66:81], v[114:117], v[110:113], v[66:81]
	ds_read_b128 v[110:113], v170 offset:45056
	v_exp_f32_e32 v114, v89
	v_exp_f32_e32 v115, v90
	v_exp_f32_e32 v116, v91
	v_exp_f32_e32 v117, v92
	v_cvt_pk_bf16_f32 v89, v121, v122
	s_waitcnt lgkmcnt(0)
	v_mfma_f32_32x32x16_bf16 v[66:81], v[110:113], v[106:109], v[66:81]
	ds_read_b128 v[106:109], v171 offset:45056
	v_exp_f32_e32 v110, v85
	v_exp_f32_e32 v111, v86
	v_exp_f32_e32 v112, v87
	v_exp_f32_e32 v113, v88
	v_cvt_pk_bf16_f32 v86, v115, v116
	v_cvt_pk_bf16_f32 v87, v117, v118
	s_waitcnt lgkmcnt(0)
	v_mfma_f32_32x32x16_bf16 v[66:81], v[106:109], v[102:105], v[66:81]
	ds_read_b128 v[102:105], v172 offset:45056
	v_exp_f32_e32 v107, v82
	v_exp_f32_e32 v108, v83
	v_exp_f32_e32 v109, v84
	v_cvt_pk_bf16_f32 v84, v111, v112
	v_cvt_pk_bf16_f32 v85, v113, v114
	v_cvt_pk_bf16_f32 v82, v107, v108
	s_waitcnt lgkmcnt(0)
	v_mfma_f32_32x32x16_bf16 v[66:81], v[102:105], v[98:101], v[66:81]
	v_cvt_pk_bf16_f32 v83, v109, v110
	v_cvt_pk_bf16_f32 v88, v119, v120
	v_lshl_add_u32 v106, s0, 14, v176
	ds_read_b64_tr_b16 v[90:91], v106 offset:0
	ds_read_b64_tr_b16 v[92:93], v106 offset:0x800
	ds_read_b64_tr_b16 v[94:95], v106 offset:0x1000
	ds_read_b64_tr_b16 v[96:97], v106 offset:0x1800
	ds_read_b64_tr_b16 v[98:99], v106 offset:0x200
	ds_read_b64_tr_b16 v[100:101], v106 offset:0xa00
	ds_read_b64_tr_b16 v[102:103], v106 offset:0x1200
	ds_read_b64_tr_b16 v[104:105], v106 offset:0x1a00
	s_waitcnt lgkmcnt(4)
	s_nop 0
	v_mfma_f32_32x32x16_bf16 v[2:17], v[82:85], v[90:93], v[2:17]
	s_nop 2
	v_exp_f32_e32 v123, v66
	v_exp_f32_e32 v124, v67
	v_exp_f32_e32 v125, v68
	v_exp_f32_e32 v126, v69
	v_mfma_f32_32x32x16_bf16 v[2:17], v[86:89], v[94:97], v[2:17]
	ds_read_b64_tr_b16 v[66:67], v106 offset:0x400
	ds_read_b64_tr_b16 v[68:69], v106 offset:0xc00
	ds_read_b64_tr_b16 v[90:91], v106 offset:0x1400
	ds_read_b64_tr_b16 v[92:93], v106 offset:0x1c00
	s_waitcnt lgkmcnt(4)
	v_mfma_f32_32x32x16_bf16 v[18:33], v[82:85], v[98:101], v[18:33]
	v_exp_f32_e32 v98, v70
	v_exp_f32_e32 v99, v71
	v_exp_f32_e32 v100, v72
	v_exp_f32_e32 v101, v73
	v_mfma_f32_32x32x16_bf16 v[18:33], v[86:89], v[102:105], v[18:33]
	ds_read_b64_tr_b16 v[70:71], v106 offset:0x600
	ds_read_b64_tr_b16 v[72:73], v106 offset:0xe00
	ds_read_b64_tr_b16 v[94:95], v106 offset:0x1600
	ds_read_b64_tr_b16 v[96:97], v106 offset:0x1e00
	s_waitcnt lgkmcnt(4)
	v_mfma_f32_32x32x16_bf16 v[34:49], v[82:85], v[66:69], v[34:49]
	v_exp_f32_e32 v102, v74
	v_exp_f32_e32 v103, v75
	v_exp_f32_e32 v104, v76
	v_exp_f32_e32 v105, v77
	v_mfma_f32_32x32x16_bf16 v[34:49], v[86:89], v[90:93], v[34:49]
	ds_read_b64_tr_b16 v[74:75], v106 offset:0x2000
	ds_read_b64_tr_b16 v[76:77], v106 offset:0x2800
	ds_read_b64_tr_b16 v[90:91], v106 offset:0x3000
	ds_read_b64_tr_b16 v[92:93], v106 offset:0x3800
	s_waitcnt lgkmcnt(4)
	v_add_f32_e32 v66, v107, v108
	v_add_f32_e32 v67, v123, v124
	v_mfma_f32_32x32x16_bf16 v[50:65], v[82:85], v[70:73], v[50:65]
	v_add_f32_e32 v66, v66, v109
	v_add_f32_e32 v67, v67, v125
	v_exp_f32_e32 v127, v78
	v_add_f32_e32 v66, v66, v110
	v_add_f32_e32 v67, v67, v126
	v_exp_f32_e32 v128, v79
	v_add_f32_e32 v66, v66, v111
	v_add_f32_e32 v67, v67, v98
	v_mfma_f32_32x32x16_bf16 v[50:65], v[86:89], v[94:97], v[50:65]
	v_add_f32_e32 v66, v66, v112
	v_add_f32_e32 v67, v67, v99
	v_exp_f32_e32 v129, v80
	v_add_f32_e32 v66, v66, v113
	v_add_f32_e32 v67, v67, v100
	v_exp_f32_e32 v81, v81
	v_add_f32_e32 v66, v66, v114
	v_add_f32_e32 v67, v67, v101
	v_cvt_pk_bf16_f32 v68, v123, v124
	v_add_f32_e32 v66, v66, v115
	v_add_f32_e32 v67, v67, v102
	v_cvt_pk_bf16_f32 v69, v125, v126
	v_add_f32_e32 v66, v66, v116
	v_add_f32_e32 v67, v67, v103
	v_cvt_pk_bf16_f32 v70, v98, v99
	v_add_f32_e32 v66, v66, v117
	v_add_f32_e32 v67, v67, v104
	v_cvt_pk_bf16_f32 v71, v100, v101
	v_add_f32_e32 v66, v66, v118
	v_add_f32_e32 v67, v67, v105
	v_cvt_pk_bf16_f32 v78, v102, v103
	v_add_f32_e32 v66, v66, v119
	v_add_f32_e32 v67, v67, v127
	v_cvt_pk_bf16_f32 v79, v104, v105
	v_add_f32_e32 v66, v66, v120
	v_add_f32_e32 v67, v67, v128
	v_cvt_pk_bf16_f32 v80, v127, v128
	v_add_f32_e32 v66, v66, v121
	v_add_f32_e32 v67, v67, v129
	v_add_f32_e32 v66, v66, v122
	v_add_f32_e32 v67, v67, v81
	v_cvt_pk_bf16_f32 v81, v129, v81
	v_add_f32_e32 v66, v66, v67
	v_add_f32_e32 v66, v151, v66
	v_mov_b32_e32 v67, v66
	s_nop 1
	v_permlane32_swap_b32_e32 v66, v67
	ds_read_b64_tr_b16 v[82:83], v106 offset:0x2200
	ds_read_b64_tr_b16 v[84:85], v106 offset:0x2a00
	ds_read_b64_tr_b16 v[86:87], v106 offset:0x3200
	ds_read_b64_tr_b16 v[88:89], v106 offset:0x3a00
	s_waitcnt lgkmcnt(4)
	v_mfma_f32_32x32x16_bf16 v[2:17], v[68:71], v[74:77], v[2:17]
	s_nop 0
	v_mfma_f32_32x32x16_bf16 v[2:17], v[78:81], v[90:93], v[2:17]
	ds_read_b64_tr_b16 v[72:73], v106 offset:0x2400
	ds_read_b64_tr_b16 v[74:75], v106 offset:0x2c00
	ds_read_b64_tr_b16 v[90:91], v106 offset:0x3400
	ds_read_b64_tr_b16 v[92:93], v106 offset:0x3c00
	s_waitcnt lgkmcnt(4)
	v_mfma_f32_32x32x16_bf16 v[18:33], v[68:71], v[82:85], v[18:33]
	v_mfma_f32_32x32x16_bf16 v[18:33], v[78:81], v[86:89], v[18:33]
	ds_read_b64_tr_b16 v[82:83], v106 offset:0x2600
	ds_read_b64_tr_b16 v[84:85], v106 offset:0x2e00
	ds_read_b64_tr_b16 v[86:87], v106 offset:0x3600
	ds_read_b64_tr_b16 v[88:89], v106 offset:0x3e00
	s_waitcnt lgkmcnt(4)
	v_mfma_f32_32x32x16_bf16 v[34:49], v[68:71], v[72:75], v[34:49]
	v_mfma_f32_32x32x16_bf16 v[34:49], v[78:81], v[90:93], v[34:49]
	s_waitcnt lgkmcnt(0)
	v_mfma_f32_32x32x16_bf16 v[50:65], v[68:71], v[82:85], v[50:65]
	s_waitcnt vmcnt(0)
	s_barrier
	v_mfma_f32_32x32x16_bf16 v[50:65], v[78:81], v[86:89], v[50:65]
	s_and_saveexec_b64 s[0:1], s[2:3]
	s_cbranch_execz .LBB0_886
	v_add_f32_e32 v66, v66, v67
	v_lshl_add_u32 v68, v1, 2, s4
	ds_write_b32 v68, v66
	s_branch .LBB0_886

.LBB0_904:
	v_add_f32_e32 v1, v1, v116
	s_add_u32 s0, s18, 0x240000
	v_add_f32_e32 v1, 0, v1
	v_add_f32_e32 v66, v66, v67
	s_addc_u32 s1, s19, 0
	v_add_f32_e32 v1, v1, v66
	v_lshl_add_u64 v[66:67], v[72:73], 1, s[0:1]
	s_mov_b32 m0, s35
	v_exp_f32_e32 v175, v106
	global_load_lds_dwordx4 v[66:67], off
	v_lshl_add_u64 v[66:67], v[70:71], 1, s[0:1]
	s_mov_b32 m0, s86
	v_exp_f32_e32 v176, v107
	global_load_lds_dwordx4 v[66:67], off
	v_exp_f32_e32 v177, v108
	v_exp_f32_e32 v178, v109
	v_exp_f32_e32 v179, v110
	v_exp_f32_e32 v180, v111
	v_exp_f32_e32 v181, v112
	v_exp_f32_e32 v192, v113
	ds_read_b128 v[66:69], v188 offset:40960
	ds_read_b128 v[70:73], v188 offset:45056
	ds_read_b128 v[106:109], v189 offset:40960
	ds_read_b128 v[110:113], v189 offset:45056
	ds_read_b128 v[116:119], v190 offset:40960
	ds_read_b128 v[120:123], v190 offset:45056
	ds_read_b128 v[124:127], v191 offset:40960
	ds_read_b128 v[170:173], v191 offset:45056
	v_exp_f32_e32 v151, v98
	v_exp_f32_e32 v153, v99
	v_exp_f32_e32 v155, v100
	v_exp_f32_e32 v157, v101
	v_exp_f32_e32 v159, v102
	v_exp_f32_e32 v161, v103
	v_exp_f32_e32 v163, v104
	v_exp_f32_e32 v174, v105
	s_waitcnt lgkmcnt(0)
	v_mfma_f32_32x32x16_bf16 v[90:105], v[66:69], v[128:131], 0
	v_exp_f32_e32 v193, v74
	v_exp_f32_e32 v194, v75
	v_exp_f32_e32 v195, v76
	v_exp_f32_e32 v196, v77
	v_exp_f32_e32 v197, v78
	v_exp_f32_e32 v198, v79
	v_exp_f32_e32 v199, v80
	v_exp_f32_e32 v200, v81
	v_mfma_f32_32x32x16_bf16 v[66:81], v[70:73], v[128:131], 0
	v_mfma_f32_32x32x16_bf16 v[90:105], v[106:109], v[132:135], v[90:105]
	v_exp_f32_e32 v82, v82
	v_exp_f32_e32 v83, v83
	v_exp_f32_e32 v84, v84
	v_exp_f32_e32 v85, v85
	v_exp_f32_e32 v86, v86
	v_exp_f32_e32 v87, v87
	v_exp_f32_e32 v88, v88
	v_mfma_f32_32x32x16_bf16 v[66:81], v[110:113], v[132:135], v[66:81]
	v_exp_f32_e32 v89, v89
	v_add_f32_e32 v106, v151, v153
	v_add_f32_e32 v107, v193, v194
	v_mfma_f32_32x32x16_bf16 v[90:105], v[116:119], v[136:139], v[90:105]
	v_add_f32_e32 v106, v106, v155
	v_add_f32_e32 v107, v107, v195
	v_cvt_pk_bf16_f32 v108, v159, v161
	v_add_f32_e32 v106, v106, v157
	v_add_f32_e32 v107, v107, v196
	v_cvt_pk_bf16_f32 v109, v163, v174
	v_add_f32_e32 v106, v106, v159
	v_add_f32_e32 v107, v107, v197
	v_mfma_f32_32x32x16_bf16 v[66:81], v[120:123], v[136:139], v[66:81]
	v_add_f32_e32 v106, v106, v161
	v_add_f32_e32 v107, v107, v198
	s_nop 0
	v_add_f32_e32 v106, v106, v163
	v_add_f32_e32 v107, v107, v199
	s_nop 0
	v_add_f32_e32 v106, v106, v174
	v_add_f32_e32 v107, v107, v200
	s_nop 0
	v_add_f32_e32 v106, v106, v175
	v_add_f32_e32 v107, v107, v82
	s_nop 0
	v_add_f32_e32 v106, v106, v176
	v_add_f32_e32 v107, v107, v83
	s_nop 0
	v_add_f32_e32 v106, v106, v177
	v_add_f32_e32 v107, v107, v84
	s_nop 0
	v_add_f32_e32 v106, v106, v178
	v_add_f32_e32 v107, v107, v85
	s_nop 0
	v_add_f32_e32 v106, v106, v179
	v_add_f32_e32 v107, v107, v86
	s_nop 0
	v_add_f32_e32 v106, v106, v180
	v_add_f32_e32 v107, v107, v87
	s_nop 0
	v_add_f32_e32 v106, v106, v181
	v_add_f32_e32 v107, v107, v88
	s_nop 0
	v_add_f32_e32 v106, v106, v192
	v_add_f32_e32 v107, v107, v89
	s_nop 0
	v_add_f32_e32 v106, v106, v107
	v_mov_b32_e32 v107, v106
	s_nop 1
	v_permlane32_swap_b32_e32 v106, v107
	v_add_f32_e32 v106, v106, v107
	v_add_f32_e32 v149, v1, v106
	v_cvt_pk_bf16_f32 v106, v151, v153
	v_cvt_pk_bf16_f32 v107, v155, v157
	v_mfma_f32_32x32x16_bf16 v[90:105], v[124:127], v[140:143], v[90:105]
	v_cvt_pk_bf16_f32 v110, v175, v176
	v_cvt_pk_bf16_f32 v111, v177, v178
	v_cvt_pk_bf16_f32 v112, v179, v180
	v_cvt_pk_bf16_f32 v113, v181, v192
	v_cvt_pk_bf16_f32 v116, v193, v194
	v_cvt_pk_bf16_f32 v117, v195, v196
	v_cvt_pk_bf16_f32 v118, v197, v198
	v_mfma_f32_32x32x16_bf16 v[66:81], v[170:173], v[140:143], v[66:81]
	v_cvt_pk_bf16_f32 v119, v199, v200
	v_cvt_pk_bf16_f32 v120, v82, v83
	v_cvt_pk_bf16_f32 v121, v84, v85
	v_cvt_pk_bf16_f32 v122, v86, v87
	v_cvt_pk_bf16_f32 v123, v88, v89
	ds_read_b64_tr_b16 v[82:83], v184 offset:0
	ds_read_b64_tr_b16 v[84:85], v184 offset:0x800
	ds_read_b64_tr_b16 v[86:87], v184 offset:0x1000
	ds_read_b64_tr_b16 v[88:89], v184 offset:0x1800
	ds_read_b64_tr_b16 v[124:125], v184 offset:0x2000
	ds_read_b64_tr_b16 v[126:127], v184 offset:0x2800
	ds_read_b64_tr_b16 v[170:171], v184 offset:0x3000
	ds_read_b64_tr_b16 v[172:173], v184 offset:0x3800
	ds_read_b64_tr_b16 v[174:175], v184 offset:0x200
	ds_read_b64_tr_b16 v[176:177], v184 offset:0xa00
	ds_read_b64_tr_b16 v[178:179], v184 offset:0x1200
	ds_read_b64_tr_b16 v[180:181], v184 offset:0x1a00
	ds_read_b64_tr_b16 v[192:193], v184 offset:0x2200
	ds_read_b64_tr_b16 v[194:195], v184 offset:0x2a00
	ds_read_b64_tr_b16 v[196:197], v184 offset:0x3200
	ds_read_b64_tr_b16 v[198:199], v184 offset:0x3a00
	s_waitcnt lgkmcnt(8)
	s_nop 0
	v_mfma_f32_32x32x16_bf16 v[2:17], v[106:109], v[82:85], v[2:17]
	v_exp_f32_e32 v1, v91
	v_exp_f32_e32 v82, v92
	v_exp_f32_e32 v83, v93
	v_mfma_f32_32x32x16_bf16 v[2:17], v[110:113], v[86:89], v[2:17]
	v_exp_f32_e32 v88, v90
	v_mfma_f32_32x32x16_bf16 v[2:17], v[116:119], v[124:127], v[2:17]
	v_mfma_f32_32x32x16_bf16 v[2:17], v[120:123], v[170:173], v[2:17]
	ds_read_b64_tr_b16 v[90:91], v184 offset:0x400
	ds_read_b64_tr_b16 v[92:93], v184 offset:0xc00
	ds_read_b64_tr_b16 v[124:125], v184 offset:0x1400
	ds_read_b64_tr_b16 v[126:127], v184 offset:0x1c00
	ds_read_b64_tr_b16 v[170:171], v184 offset:0x2400
	ds_read_b64_tr_b16 v[172:173], v184 offset:0x2c00
	ds_read_b64_tr_b16 v[200:201], v184 offset:0x3400
	ds_read_b64_tr_b16 v[202:203], v184 offset:0x3c00
	s_waitcnt lgkmcnt(8)
	v_mfma_f32_32x32x16_bf16 v[18:33], v[106:109], v[174:177], v[18:33]
	v_exp_f32_e32 v84, v94
	v_exp_f32_e32 v85, v95
	v_exp_f32_e32 v86, v96
	v_exp_f32_e32 v87, v97
	v_mfma_f32_32x32x16_bf16 v[18:33], v[110:113], v[178:181], v[18:33]
	v_mfma_f32_32x32x16_bf16 v[18:33], v[116:119], v[192:195], v[18:33]
	v_mfma_f32_32x32x16_bf16 v[18:33], v[120:123], v[196:199], v[18:33]
	ds_read_b64_tr_b16 v[94:95], v184 offset:0x600
	ds_read_b64_tr_b16 v[96:97], v184 offset:0xe00
	ds_read_b64_tr_b16 v[174:175], v184 offset:0x1600
	ds_read_b64_tr_b16 v[176:177], v184 offset:0x1e00
	ds_read_b64_tr_b16 v[178:179], v184 offset:0x2600
	ds_read_b64_tr_b16 v[180:181], v184 offset:0x2e00
	ds_read_b64_tr_b16 v[192:193], v184 offset:0x3600
	ds_read_b64_tr_b16 v[194:195], v184 offset:0x3e00
	s_waitcnt lgkmcnt(8)
	v_mfma_f32_32x32x16_bf16 v[34:49], v[106:109], v[90:93], v[34:49]
	v_exp_f32_e32 v90, v98
	v_exp_f32_e32 v89, v99
	v_exp_f32_e32 v92, v100
	v_exp_f32_e32 v91, v101
	v_mfma_f32_32x32x16_bf16 v[34:49], v[110:113], v[124:127], v[34:49]
	v_mfma_f32_32x32x16_bf16 v[34:49], v[116:119], v[170:173], v[34:49]
	v_mfma_f32_32x32x16_bf16 v[34:49], v[120:123], v[200:203], v[34:49]
	s_waitcnt lgkmcnt(0)
	v_mfma_f32_32x32x16_bf16 v[50:65], v[106:109], v[94:97], v[50:65]
	v_exp_f32_e32 v94, v102
	v_exp_f32_e32 v93, v103
	v_exp_f32_e32 v95, v104
	v_exp_f32_e32 v151, v105
	v_mfma_f32_32x32x16_bf16 v[50:65], v[110:113], v[174:177], v[50:65]
	v_mfma_f32_32x32x16_bf16 v[50:65], v[116:119], v[178:181], v[50:65]
	v_mfma_f32_32x32x16_bf16 v[50:65], v[120:123], v[192:195], v[50:65]
	s_waitcnt vmcnt(0)
	s_and_b64 vcc, exec, s[4:5]
	s_waitcnt vmcnt(0)
	s_barrier
	s_cbranch_vccnz .LBB0_911
	v_readlane_b32 s36, v243, 63
	v_readlane_b32 s50, v242, 13
	v_readlane_b32 s51, v242, 14
	s_add_u32 s4, s50, s88
	v_mov_b32_e32 v96, s25
	v_mov_b32_e32 v97, v145
	s_addc_u32 s5, s51, s87
	s_add_i32 s92, s92, s91
	v_lshl_add_u64 v[170:171], v[114:115], 1, v[96:97]
	v_add_u32_e32 v96, s92, v182
	v_add_u32_e32 v97, s10, v166
	v_lshrrev_b32_e32 v98, 1, v96
	v_xor_b32_e32 v98, v98, v96
	v_and_b32_e32 v98, 4, v98
	v_lshl_or_b32 v98, v98, 1, v98
	v_xor_b32_e32 v96, v96, v98
	v_mul_lo_u32 v96, v96, s22
	v_and_b32_e32 v98, 0x60, v97
	v_or3_b32 v96, v169, v96, v98
	v_ashrrev_i32_e32 v97, 31, v96
	s_add_i32 s90, s90, s89
	v_lshlrev_b64 v[172:173], 1, v[96:97]
	v_add_u32_e32 v96, s90, v182
	v_lshrrev_b32_e32 v97, 1, v96
	v_xor_b32_e32 v97, v97, v96
	v_and_b32_e32 v97, 4, v97
	v_lshl_or_b32 v97, v97, 1, v97
	v_xor_b32_e32 v96, v96, v97
	v_mul_lo_u32 v96, v96, s22
	v_or3_b32 v96, v169, v96, v98
	v_ashrrev_i32_e32 v97, 31, v96
	v_lshlrev_b64 v[174:175], 1, v[96:97]
	v_or_b32_e32 v172, s24, v172
	v_or_b32_e32 v174, s24, v174
	s_mov_b32 s16, 6
	v_readlane_b32 s37, v242, 0
	v_readlane_b32 s38, v242, 1
	v_readlane_b32 s39, v242, 2
	v_readlane_b32 s40, v242, 3
	v_readlane_b32 s41, v242, 4
	v_readlane_b32 s42, v242, 5
	v_readlane_b32 s43, v242, 6
	v_readlane_b32 s44, v242, 7
	v_readlane_b32 s45, v242, 8
	v_readlane_b32 s46, v242, 9
	v_readlane_b32 s47, v242, 10
	v_readlane_b32 s48, v242, 11
	v_readlane_b32 s49, v242, 12
	v_exp_f32_e32 v222, v66
	v_exp_f32_e32 v223, v67
	v_exp_f32_e32 v224, v68
	v_exp_f32_e32 v225, v69
	v_exp_f32_e32 v226, v70
	v_exp_f32_e32 v227, v71
	v_exp_f32_e32 v228, v72
	v_exp_f32_e32 v229, v73
	v_exp_f32_e32 v230, v74
	v_exp_f32_e32 v231, v75
	v_exp_f32_e32 v232, v76
	v_exp_f32_e32 v233, v77
	v_exp_f32_e32 v234, v78
	v_exp_f32_e32 v235, v79
	v_exp_f32_e32 v236, v80
	v_exp_f32_e32 v237, v81
	s_branch .LBB0_907

.LBB0_909:
	v_lshl_add_u64 v[178:179], s[4:5], 0, v[172:173]
	s_mov_b32 m0, s30
	v_lshl_add_u64 v[96:97], v[178:179], 0, s[8:9]
	v_lshl_add_u64 v[176:177], s[4:5], 0, v[174:175]
	global_load_lds_dwordx4 v[96:97], off
	v_lshl_add_u64 v[96:97], v[176:177], 0, s[8:9]
	s_mov_b32 m0, s33
	s_nop 0
	global_load_lds_dwordx4 v[96:97], off
	ds_read_b128 v[96:99], v188 offset:32768
	ds_read_b128 v[100:103], v188 offset:36864
	ds_read_b128 v[192:195], v189 offset:32768
	ds_read_b128 v[196:199], v189 offset:36864
	ds_read_b128 v[200:203], v190 offset:32768
	ds_read_b128 v[204:207], v190 offset:36864
	ds_read_b128 v[208:211], v191 offset:32768
	ds_read_b128 v[212:215], v191 offset:36864
	s_waitcnt lgkmcnt(0)
	v_mfma_f32_32x32x16_bf16 v[112:127], v[96:99], v[128:131], 0
	v_mfma_f32_32x32x16_bf16 v[96:111], v[100:103], v[128:131], 0
	v_mfma_f32_32x32x16_bf16 v[112:127], v[192:195], v[132:135], v[112:127]
	v_mfma_f32_32x32x16_bf16 v[96:111], v[196:199], v[132:135], v[96:111]
	v_add_f32_e32 v67, v88, v1
	v_cvt_pk_bf16_f32 v66, v88, v1
	v_add_f32_e32 v1, v222, v223
	v_add_f32_e32 v67, v67, v82
	v_mfma_f32_32x32x16_bf16 v[112:127], v[200:203], v[136:139], v[112:127]
	v_add_f32_e32 v1, v1, v224
	v_add_f32_e32 v67, v67, v83
	v_cvt_pk_bf16_f32 v68, v84, v85
	v_add_f32_e32 v1, v1, v225
	v_add_f32_e32 v67, v67, v84
	v_cvt_pk_bf16_f32 v69, v86, v87
	v_add_f32_e32 v1, v1, v226
	v_add_f32_e32 v67, v67, v85
	v_mfma_f32_32x32x16_bf16 v[96:111], v[204:207], v[136:139], v[96:111]
	v_add_f32_e32 v1, v1, v227
	v_add_f32_e32 v67, v67, v86
	v_add_f32_e32 v1, v1, v228
	v_add_f32_e32 v67, v67, v87
	v_add_f32_e32 v1, v1, v229
	v_add_f32_e32 v67, v67, v90
	v_add_f32_e32 v1, v1, v230
	v_add_f32_e32 v67, v67, v89
	v_add_f32_e32 v1, v1, v231
	v_add_f32_e32 v67, v67, v92
	v_add_f32_e32 v1, v1, v232
	v_add_f32_e32 v67, v67, v91
	v_add_f32_e32 v1, v1, v233
	v_add_f32_e32 v67, v67, v94
	v_add_f32_e32 v1, v1, v234
	v_add_f32_e32 v67, v67, v93
	v_add_f32_e32 v1, v1, v235
	v_add_f32_e32 v67, v67, v95
	v_add_f32_e32 v1, v1, v236
	v_add_f32_e32 v67, v67, v151
	v_add_f32_e32 v1, v1, v237
	v_add_f32_e32 v1, v67, v1
	v_mov_b32_e32 v70, v1
	s_nop 1
	v_permlane32_swap_b32_e32 v1, v70
	v_cvt_pk_bf16_f32 v67, v82, v83
	v_mfma_f32_32x32x16_bf16 v[112:127], v[208:211], v[140:143], v[112:127]
	v_cvt_pk_bf16_f32 v72, v90, v89
	v_cvt_pk_bf16_f32 v73, v92, v91
	v_cvt_pk_bf16_f32 v74, v94, v93
	v_cvt_pk_bf16_f32 v75, v95, v151
	v_cvt_pk_bf16_f32 v76, v222, v223
	v_cvt_pk_bf16_f32 v77, v224, v225
	v_cvt_pk_bf16_f32 v78, v226, v227
	v_mfma_f32_32x32x16_bf16 v[96:111], v[212:215], v[140:143], v[96:111]
	v_cvt_pk_bf16_f32 v79, v228, v229
	v_cvt_pk_bf16_f32 v80, v230, v231
	v_cvt_pk_bf16_f32 v81, v232, v233
	v_cvt_pk_bf16_f32 v82, v234, v235
	v_cvt_pk_bf16_f32 v83, v236, v237
	ds_read_b64_tr_b16 v[84:85], v185 offset:0
	ds_read_b64_tr_b16 v[86:87], v185 offset:0x800
	ds_read_b64_tr_b16 v[88:89], v185 offset:0x1000
	ds_read_b64_tr_b16 v[90:91], v185 offset:0x1800
	ds_read_b64_tr_b16 v[92:93], v185 offset:0x2000
	ds_read_b64_tr_b16 v[94:95], v185 offset:0x2800
	ds_read_b64_tr_b16 v[192:193], v185 offset:0x3000
	ds_read_b64_tr_b16 v[194:195], v185 offset:0x3800
	ds_read_b64_tr_b16 v[196:197], v185 offset:0x200
	ds_read_b64_tr_b16 v[198:199], v185 offset:0xa00
	ds_read_b64_tr_b16 v[200:201], v185 offset:0x1200
	ds_read_b64_tr_b16 v[202:203], v185 offset:0x1a00
	ds_read_b64_tr_b16 v[204:205], v185 offset:0x2200
	ds_read_b64_tr_b16 v[206:207], v185 offset:0x2a00
	ds_read_b64_tr_b16 v[208:209], v185 offset:0x3200
	ds_read_b64_tr_b16 v[210:211], v185 offset:0x3a00
	s_waitcnt lgkmcnt(8)
	s_nop 0
	v_mfma_f32_32x32x16_bf16 v[2:17], v[66:69], v[84:87], v[2:17]
	v_exp_f32_e32 v238, v112
	v_exp_f32_e32 v239, v113
	v_mfma_f32_32x32x16_bf16 v[2:17], v[72:75], v[88:91], v[2:17]
	v_exp_f32_e32 v240, v114
	v_exp_f32_e32 v241, v115
	v_mfma_f32_32x32x16_bf16 v[2:17], v[76:79], v[92:95], v[2:17]
	v_exp_f32_e32 v244, v116
	v_exp_f32_e32 v245, v117
	v_mfma_f32_32x32x16_bf16 v[2:17], v[80:83], v[192:195], v[2:17]
	v_exp_f32_e32 v246, v118
	v_exp_f32_e32 v247, v119
	ds_read_b64_tr_b16 v[84:85], v185 offset:0x400
	ds_read_b64_tr_b16 v[86:87], v185 offset:0xc00
	ds_read_b64_tr_b16 v[88:89], v185 offset:0x1400
	ds_read_b64_tr_b16 v[90:91], v185 offset:0x1c00
	ds_read_b64_tr_b16 v[92:93], v185 offset:0x2400
	ds_read_b64_tr_b16 v[94:95], v185 offset:0x2c00
	ds_read_b64_tr_b16 v[192:193], v185 offset:0x3400
	ds_read_b64_tr_b16 v[194:195], v185 offset:0x3c00
	s_waitcnt lgkmcnt(8)
	v_mfma_f32_32x32x16_bf16 v[18:33], v[66:69], v[196:199], v[18:33]
	v_exp_f32_e32 v248, v120
	v_exp_f32_e32 v249, v121
	v_mfma_f32_32x32x16_bf16 v[18:33], v[72:75], v[200:203], v[18:33]
	v_exp_f32_e32 v250, v122
	v_exp_f32_e32 v251, v123
	v_mfma_f32_32x32x16_bf16 v[18:33], v[76:79], v[204:207], v[18:33]
	v_exp_f32_e32 v252, v124
	v_exp_f32_e32 v253, v125
	v_mfma_f32_32x32x16_bf16 v[18:33], v[80:83], v[208:211], v[18:33]
	v_exp_f32_e32 v254, v126
	v_exp_f32_e32 v255, v127
	ds_read_b64_tr_b16 v[196:197], v185 offset:0x600
	ds_read_b64_tr_b16 v[198:199], v185 offset:0xe00
	ds_read_b64_tr_b16 v[200:201], v185 offset:0x1600
	ds_read_b64_tr_b16 v[202:203], v185 offset:0x1e00
	ds_read_b64_tr_b16 v[204:205], v185 offset:0x2600
	ds_read_b64_tr_b16 v[206:207], v185 offset:0x2e00
	ds_read_b64_tr_b16 v[208:209], v185 offset:0x3600
	ds_read_b64_tr_b16 v[210:211], v185 offset:0x3e00
	s_waitcnt lgkmcnt(8)
	v_mfma_f32_32x32x16_bf16 v[34:49], v[66:69], v[84:87], v[34:49]
	v_exp_f32_e32 v222, v96
	v_exp_f32_e32 v223, v97
	v_mfma_f32_32x32x16_bf16 v[34:49], v[72:75], v[88:91], v[34:49]
	v_exp_f32_e32 v224, v98
	v_exp_f32_e32 v225, v99
	v_mfma_f32_32x32x16_bf16 v[34:49], v[76:79], v[92:95], v[34:49]
	v_exp_f32_e32 v226, v100
	v_exp_f32_e32 v227, v101
	v_mfma_f32_32x32x16_bf16 v[34:49], v[80:83], v[192:195], v[34:49]
	v_exp_f32_e32 v228, v102
	v_exp_f32_e32 v229, v103
	s_waitcnt lgkmcnt(0)
	v_mfma_f32_32x32x16_bf16 v[50:65], v[66:69], v[196:199], v[50:65]
	v_exp_f32_e32 v230, v104
	v_exp_f32_e32 v231, v105
	v_mfma_f32_32x32x16_bf16 v[50:65], v[72:75], v[200:203], v[50:65]
	v_exp_f32_e32 v232, v106
	v_exp_f32_e32 v233, v107
	v_mfma_f32_32x32x16_bf16 v[50:65], v[76:79], v[204:207], v[50:65]
	v_exp_f32_e32 v234, v108
	v_exp_f32_e32 v235, v109
	v_mfma_f32_32x32x16_bf16 v[50:65], v[80:83], v[208:211], v[50:65]
	v_exp_f32_e32 v236, v110
	v_exp_f32_e32 v237, v111
	s_waitcnt vmcnt(0)
	s_cmp_ge_u32 s16, s11
	s_cselect_b64 s[0:1], -1, 0
	s_and_b64 vcc, exec, s[0:1]
	s_waitcnt vmcnt(0)
	s_barrier
	s_cbranch_vccnz .LBB0_906
	s_mov_b64 s[18:19], 0x15c81800
	v_lshl_add_u64 v[66:67], v[180:181], 0, s[18:19]
	s_mov_b32 m0, s31
	s_nop 0
	global_load_lds_dwordx4 v[66:67], off
	s_branch .LBB0_906

.LBB0_2312:
	v_add_co_u32_e64 v66, s[14:15], s4, 3
	s_nop 0
	v_readfirstlane_b32 s21, v66
	s_and_b32 s21, s21, 1
	s_lshl_b64 s[28:29], s[4:5], 6
	s_and_b64 s[40:41], s[14:15], exec
	s_cselect_b32 s29, s1, s29
	s_cselect_b32 s28, s0, s28
	s_mul_i32 s42, s29, 0xc00
	s_mul_hi_u32 s43, s28, 0xc00
	s_cselect_b32 s41, s13, s39
	s_cselect_b32 s40, s12, s38
	s_add_i32 s43, s43, s42
	s_mul_i32 s42, s28, 0xc00
	s_add_u32 s40, s40, s42
	s_addc_u32 s41, s41, s43
	s_xor_b32 s42, s21, 1
	s_mulk_i32 s42, 0x6000
	s_add_i32 s42, s53, s42
	s_add_i32 m0, s42, 0x8000
	s_nop 0
	global_load_lds_dwordx4 v238, s[40:41]
	s_add_i32 m0, s42, 0xa000
	s_lshl_b64 s[28:29], s[28:29], 12
	global_load_lds_dwordx4 v239, s[40:41]
	s_add_i32 m0, s42, 0xc000
	s_and_b64 s[14:15], s[14:15], exec
	s_cselect_b32 s14, s44, s46
	s_cselect_b32 s15, s45, s47
	s_add_u32 s14, s14, s28
	s_addc_u32 s15, s15, s29
	s_lshl_b32 s28, s21, 14
	s_xor_b32 s29, s28, 0x4000
	s_add_i32 s29, s53, s29
	global_load_lds_dwordx4 v240, s[40:41]
	s_mov_b32 m0, s29
	s_mulk_i32 s21, 0x6000
	global_load_lds_dwordx4 v241, s[14:15]
	s_add_i32 m0, s29, 0x2000
	s_nop 0
	global_load_lds_dwordx4 v244, s[14:15]
	v_add_u32_e32 v74, s21, v182
	v_add_u32_e32 v75, v74, v181
	ds_read_b128 v[66:69], v75 offset:32768
	v_add_u32_e32 v76, v74, v183
	ds_read_b128 v[70:73], v76 offset:32768
	v_add_u32_e32 v153, v74, v184
	v_add_u32_e32 v155, v74, v185
	v_add_u32_e32 v157, v74, v186
	v_add_u32_e32 v159, v74, v187
	v_add_u32_e32 v209, v74, v188
	v_add_u32_e32 v218, v74, v189
	s_waitcnt lgkmcnt(0)
	v_mfma_f32_32x32x16_bf16 v[82:97], v[66:69], v[142:145], 0
	ds_read_b128 v[66:69], v153 offset:32768
	v_add_u32_e32 v219, v74, v190
	v_add_u32_e32 v220, v74, v191
	v_add_u32_e32 v221, v74, v192
	v_add_u32_e32 v222, v74, v193
	v_mfma_f32_32x32x16_bf16 v[82:97], v[70:73], v[138:141], v[82:97]
	ds_read_b128 v[70:73], v155 offset:32768
	s_waitcnt lgkmcnt(0)
	v_mfma_f32_32x32x16_bf16 v[82:97], v[66:69], v[134:137], v[82:97]
	ds_read_b128 v[66:69], v157 offset:32768
	v_mfma_f32_32x32x16_bf16 v[82:97], v[70:73], v[130:133], v[82:97]
	ds_read_b128 v[70:73], v159 offset:32768
	s_waitcnt lgkmcnt(0)
	v_mfma_f32_32x32x16_bf16 v[82:97], v[66:69], v[126:129], v[82:97]
	ds_read_b128 v[66:69], v209 offset:32768
	v_mfma_f32_32x32x16_bf16 v[82:97], v[70:73], v[122:125], v[82:97]
	ds_read_b128 v[70:73], v218 offset:32768
	s_waitcnt lgkmcnt(0)
	v_mfma_f32_32x32x16_bf16 v[82:97], v[66:69], v[118:121], v[82:97]
	ds_read_b128 v[66:69], v219 offset:32768
	v_mfma_f32_32x32x16_bf16 v[82:97], v[70:73], v[114:117], v[82:97]
	ds_read_b128 v[70:73], v220 offset:32768
	s_waitcnt lgkmcnt(0)
	v_mfma_f32_32x32x16_bf16 v[82:97], v[66:69], v[110:113], v[82:97]
	ds_read_b128 v[66:69], v221 offset:32768
	v_mfma_f32_32x32x16_bf16 v[82:97], v[70:73], v[106:109], v[82:97]
	ds_read_b128 v[70:73], v222 offset:32768
	s_waitcnt lgkmcnt(0)
	v_mfma_f32_32x32x16_bf16 v[82:97], v[66:69], v[102:105], v[82:97]
	v_mfma_f32_32x32x16_bf16 v[82:97], v[70:73], v[98:101], v[82:97]
	ds_read_b128 v[66:69], v75 offset:45056
	ds_read_b128 v[210:213], v76 offset:45056
	s_nop 9
	v_exp_f32_e32 v226, v86
	v_exp_f32_e32 v227, v87
	v_exp_f32_e32 v228, v88
	s_waitcnt lgkmcnt(0)
	v_mfma_f32_32x32x16_bf16 v[66:81], v[66:69], v[142:145], 0
	v_exp_f32_e32 v229, v89
	v_exp_f32_e32 v230, v90
	v_exp_f32_e32 v231, v91
	v_exp_f32_e32 v232, v92
	v_exp_f32_e32 v233, v93
	v_exp_f32_e32 v234, v94
	v_exp_f32_e32 v235, v95
	v_mfma_f32_32x32x16_bf16 v[66:81], v[210:213], v[138:141], v[66:81]
	ds_read_b128 v[210:213], v153 offset:45056
	ds_read_b128 v[214:217], v155 offset:45056
	v_exp_f32_e32 v155, v82
	v_exp_f32_e32 v236, v96
	v_exp_f32_e32 v237, v97
	v_cvt_pk_bf16_f32 v86, v230, v231
	v_cvt_pk_bf16_f32 v87, v232, v233
	v_cvt_pk_bf16_f32 v88, v234, v235
	s_waitcnt lgkmcnt(0)
	v_mfma_f32_32x32x16_bf16 v[66:81], v[210:213], v[134:137], v[66:81]
	v_cvt_pk_bf16_f32 v89, v236, v237
	v_add_u32_e32 v153, s28, v179
	v_mfma_f32_32x32x16_bf16 v[66:81], v[214:217], v[130:133], v[66:81]
	ds_read_b128 v[210:213], v157 offset:45056
	ds_read_b128 v[214:217], v159 offset:45056
	v_exp_f32_e32 v157, v83
	v_exp_f32_e32 v159, v84
	v_cvt_pk_bf16_f32 v84, v226, v227
	v_cvt_pk_bf16_f32 v82, v155, v157
	s_waitcnt lgkmcnt(0)
	v_mfma_f32_32x32x16_bf16 v[66:81], v[210:213], v[126:129], v[66:81]
	v_mfma_f32_32x32x16_bf16 v[66:81], v[214:217], v[122:125], v[66:81]
	ds_read_b128 v[210:213], v209 offset:45056
	ds_read_b128 v[214:217], v218 offset:45056
	v_exp_f32_e32 v209, v85
	v_cvt_pk_bf16_f32 v85, v228, v229
	v_cvt_pk_bf16_f32 v83, v159, v209
	s_waitcnt lgkmcnt(0)
	v_mfma_f32_32x32x16_bf16 v[66:81], v[210:213], v[118:121], v[66:81]
	ds_read_b128 v[210:213], v219 offset:45056
	v_mfma_f32_32x32x16_bf16 v[66:81], v[214:217], v[114:117], v[66:81]
	ds_read_b128 v[214:217], v220 offset:45056
	ds_read_b128 v[218:221], v221 offset:45056
	ds_read_b128 v[222:225], v222 offset:45056
	s_waitcnt lgkmcnt(0)
	v_mfma_f32_32x32x16_bf16 v[66:81], v[210:213], v[110:113], v[66:81]
	v_mfma_f32_32x32x16_bf16 v[66:81], v[214:217], v[106:109], v[66:81]
	v_mfma_f32_32x32x16_bf16 v[66:81], v[218:221], v[102:105], v[66:81]
	v_mfma_f32_32x32x16_bf16 v[66:81], v[222:225], v[98:101], v[66:81]
	ds_read_b64_tr_b16 v[90:91], v153 offset:0
	ds_read_b64_tr_b16 v[92:93], v153 offset:0x800
	ds_read_b64_tr_b16 v[94:95], v153 offset:0x1000
	ds_read_b64_tr_b16 v[96:97], v153 offset:0x1800
	ds_read_b64_tr_b16 v[210:211], v153 offset:0x200
	ds_read_b64_tr_b16 v[212:213], v153 offset:0xa00
	ds_read_b64_tr_b16 v[214:215], v153 offset:0x1200
	ds_read_b64_tr_b16 v[216:217], v153 offset:0x1a00
	s_waitcnt lgkmcnt(4)
	s_nop 0
	v_mfma_f32_32x32x16_bf16 v[2:17], v[82:85], v[90:93], v[2:17]
	s_nop 9
	v_exp_f32_e32 v218, v66
	v_exp_f32_e32 v219, v67
	v_exp_f32_e32 v220, v68
	v_exp_f32_e32 v221, v69
	v_mfma_f32_32x32x16_bf16 v[2:17], v[86:89], v[94:97], v[2:17]
	ds_read_b64_tr_b16 v[66:67], v153 offset:0x400
	ds_read_b64_tr_b16 v[68:69], v153 offset:0xc00
	ds_read_b64_tr_b16 v[90:91], v153 offset:0x1400
	ds_read_b64_tr_b16 v[92:93], v153 offset:0x1c00
	s_waitcnt lgkmcnt(4)
	v_mfma_f32_32x32x16_bf16 v[18:33], v[82:85], v[210:213], v[18:33]
	v_exp_f32_e32 v210, v70
	v_exp_f32_e32 v211, v71
	v_exp_f32_e32 v212, v72
	v_exp_f32_e32 v213, v73
	v_mfma_f32_32x32x16_bf16 v[18:33], v[86:89], v[214:217], v[18:33]
	ds_read_b64_tr_b16 v[70:71], v153 offset:0x600
	ds_read_b64_tr_b16 v[72:73], v153 offset:0xe00
	ds_read_b64_tr_b16 v[94:95], v153 offset:0x1600
	ds_read_b64_tr_b16 v[96:97], v153 offset:0x1e00
	s_waitcnt lgkmcnt(4)
	v_mfma_f32_32x32x16_bf16 v[34:49], v[82:85], v[66:69], v[34:49]
	v_exp_f32_e32 v214, v74
	v_exp_f32_e32 v215, v75
	v_exp_f32_e32 v216, v76
	v_exp_f32_e32 v217, v77
	v_mfma_f32_32x32x16_bf16 v[34:49], v[86:89], v[90:93], v[34:49]
	ds_read_b64_tr_b16 v[66:67], v153 offset:0x2000
	ds_read_b64_tr_b16 v[68:69], v153 offset:0x2800
	ds_read_b64_tr_b16 v[74:75], v153 offset:0x3000
	ds_read_b64_tr_b16 v[76:77], v153 offset:0x3800
	s_waitcnt lgkmcnt(4)
	v_exp_f32_e32 v90, v78
	v_mfma_f32_32x32x16_bf16 v[50:65], v[82:85], v[70:73], v[50:65]
	v_exp_f32_e32 v91, v79
	v_cvt_pk_bf16_f32 v72, v210, v211
	v_cvt_pk_bf16_f32 v73, v212, v213
	v_mfma_f32_32x32x16_bf16 v[50:65], v[86:89], v[94:97], v[50:65]
	v_exp_f32_e32 v92, v80
	v_exp_f32_e32 v248, v81
	v_cvt_pk_bf16_f32 v78, v214, v215
	v_cvt_pk_bf16_f32 v79, v216, v217
	v_cvt_pk_bf16_f32 v80, v90, v91
	v_cvt_pk_bf16_f32 v70, v218, v219
	v_cvt_pk_bf16_f32 v71, v220, v221
	v_cvt_pk_bf16_f32 v81, v92, v248
	ds_read_b64_tr_b16 v[82:83], v153 offset:0x2200
	ds_read_b64_tr_b16 v[84:85], v153 offset:0x2a00
	ds_read_b64_tr_b16 v[86:87], v153 offset:0x3200
	ds_read_b64_tr_b16 v[88:89], v153 offset:0x3a00
	s_waitcnt lgkmcnt(4)
	s_nop 0
	v_mfma_f32_32x32x16_bf16 v[2:17], v[70:73], v[66:69], v[2:17]
	v_add_f32_e32 v246, v155, v157
	v_add_f32_e32 v247, v218, v219
	v_add_f32_e32 v246, v246, v159
	v_add_f32_e32 v247, v247, v220
	v_mfma_f32_32x32x16_bf16 v[2:17], v[78:81], v[74:77], v[2:17]
	v_add_f32_e32 v246, v246, v209
	v_add_f32_e32 v247, v247, v221
	v_add_f32_e32 v246, v246, v226
	v_add_f32_e32 v247, v247, v210
	ds_read_b64_tr_b16 v[66:67], v153 offset:0x2400
	ds_read_b64_tr_b16 v[68:69], v153 offset:0x2c00
	ds_read_b64_tr_b16 v[74:75], v153 offset:0x3400
	ds_read_b64_tr_b16 v[76:77], v153 offset:0x3c00
	s_waitcnt lgkmcnt(4)
	v_mfma_f32_32x32x16_bf16 v[18:33], v[70:73], v[82:85], v[18:33]
	v_add_f32_e32 v246, v246, v227
	v_add_f32_e32 v247, v247, v211
	v_add_f32_e32 v246, v246, v228
	v_add_f32_e32 v247, v247, v212
	v_mfma_f32_32x32x16_bf16 v[18:33], v[78:81], v[86:89], v[18:33]
	v_add_f32_e32 v246, v246, v229
	v_add_f32_e32 v247, v247, v213
	v_add_f32_e32 v246, v246, v230
	v_add_f32_e32 v247, v247, v214
	ds_read_b64_tr_b16 v[82:83], v153 offset:0x2600
	ds_read_b64_tr_b16 v[84:85], v153 offset:0x2e00
	ds_read_b64_tr_b16 v[86:87], v153 offset:0x3600
	ds_read_b64_tr_b16 v[88:89], v153 offset:0x3e00
	s_waitcnt lgkmcnt(4)
	v_mfma_f32_32x32x16_bf16 v[34:49], v[70:73], v[66:69], v[34:49]
	v_add_f32_e32 v246, v246, v231
	v_add_f32_e32 v247, v247, v215
	v_add_f32_e32 v246, v246, v232
	v_add_f32_e32 v247, v247, v216
	v_mfma_f32_32x32x16_bf16 v[34:49], v[78:81], v[74:77], v[34:49]
	v_add_f32_e32 v246, v246, v233
	v_add_f32_e32 v247, v247, v217
	v_add_f32_e32 v246, v246, v234
	v_add_f32_e32 v247, v247, v90
	s_waitcnt lgkmcnt(0)
	v_mfma_f32_32x32x16_bf16 v[50:65], v[70:73], v[82:85], v[50:65]
	v_add_f32_e32 v246, v246, v235
	v_add_f32_e32 v247, v247, v91
	v_add_f32_e32 v246, v246, v236
	v_add_f32_e32 v247, v247, v92
	v_add_f32_e32 v246, v246, v237
	v_add_f32_e32 v247, v247, v248
	v_add_f32_e32 v246, v246, v247
	v_add_f32_e32 v151, v151, v246
	s_waitcnt vmcnt(0)
	s_add_u32 s0, s0, 64
	s_addc_u32 s1, s1, 0
	s_add_i32 s4, s4, 1
	s_cmpk_eq_i32 s0, 0x4100
	s_waitcnt vmcnt(0)
	s_barrier
	v_mfma_f32_32x32x16_bf16 v[50:65], v[78:81], v[86:89], v[50:65]
	s_cbranch_scc0 .LBB0_2312
	s_lshl_b32 s0, s52, 2
	s_add_i32 s4, s0, 0
	s_add_i32 s4, s4, 0x1e000
	ds_read_b128 v[66:69], v196
	ds_read_b128 v[70:73], v197
	s_waitcnt lgkmcnt(1)
	v_mfma_f32_32x32x16_bf16 v[82:97], v[66:69], v[142:145], 0
	s_waitcnt lgkmcnt(0)
	v_mfma_f32_32x32x16_bf16 v[82:97], v[70:73], v[138:141], v[82:97]
	ds_read_b128 v[66:69], v198
	ds_read_b128 v[70:73], v199
	s_waitcnt lgkmcnt(1)
	v_mfma_f32_32x32x16_bf16 v[82:97], v[66:69], v[134:137], v[82:97]
	s_waitcnt lgkmcnt(0)
	v_mfma_f32_32x32x16_bf16 v[82:97], v[70:73], v[130:133], v[82:97]
	ds_read_b128 v[66:69], v200
	ds_read_b128 v[70:73], v201
	s_waitcnt lgkmcnt(1)
	v_mfma_f32_32x32x16_bf16 v[82:97], v[66:69], v[126:129], v[82:97]
	s_waitcnt lgkmcnt(0)
	v_mfma_f32_32x32x16_bf16 v[82:97], v[70:73], v[122:125], v[82:97]
	ds_read_b128 v[66:69], v202
	ds_read_b128 v[70:73], v203
	s_waitcnt lgkmcnt(1)
	v_mfma_f32_32x32x16_bf16 v[82:97], v[66:69], v[118:121], v[82:97]
	s_waitcnt lgkmcnt(0)
	v_mfma_f32_32x32x16_bf16 v[82:97], v[70:73], v[114:117], v[82:97]
	ds_read_b128 v[66:69], v204
	ds_read_b128 v[70:73], v205
	s_waitcnt lgkmcnt(1)
	v_mfma_f32_32x32x16_bf16 v[82:97], v[66:69], v[110:113], v[82:97]
	s_waitcnt lgkmcnt(0)
	v_mfma_f32_32x32x16_bf16 v[82:97], v[70:73], v[106:109], v[82:97]
	ds_read_b128 v[66:69], v206
	ds_read_b128 v[70:73], v207
	s_waitcnt lgkmcnt(1)
	v_mfma_f32_32x32x16_bf16 v[82:97], v[66:69], v[102:105], v[82:97]
	s_waitcnt lgkmcnt(0)
	v_mfma_f32_32x32x16_bf16 v[82:97], v[70:73], v[98:101], v[82:97]
	ds_read_b128 v[66:69], v196 offset:12288
	ds_read_b128 v[160:163], v197 offset:12288
	s_waitcnt lgkmcnt(1)
	v_mfma_f32_32x32x16_bf16 v[66:81], v[66:69], v[142:145], 0
	s_waitcnt lgkmcnt(0)
	v_mfma_f32_32x32x16_bf16 v[66:81], v[160:163], v[138:141], v[66:81]
	ds_read_b128 v[138:141], v198 offset:12288
	ds_read_b128 v[142:145], v199 offset:12288
	s_waitcnt lgkmcnt(1)
	v_mfma_f32_32x32x16_bf16 v[66:81], v[138:141], v[134:137], v[66:81]
	s_waitcnt lgkmcnt(0)
	v_mfma_f32_32x32x16_bf16 v[66:81], v[142:145], v[130:133], v[66:81]
	ds_read_b128 v[130:133], v200 offset:12288
	ds_read_b128 v[134:137], v201 offset:12288
	s_waitcnt lgkmcnt(1)
	v_mfma_f32_32x32x16_bf16 v[66:81], v[130:133], v[126:129], v[66:81]
	v_exp_f32_e32 v130, v82
	v_exp_f32_e32 v131, v83
	v_exp_f32_e32 v132, v84
	v_cvt_pk_bf16_f32 v82, v130, v131
	s_waitcnt lgkmcnt(0)
	v_mfma_f32_32x32x16_bf16 v[66:81], v[134:137], v[122:125], v[66:81]
	ds_read_b128 v[122:125], v202 offset:12288
	ds_read_b128 v[126:129], v203 offset:12288
	s_waitcnt lgkmcnt(1)
	v_mfma_f32_32x32x16_bf16 v[66:81], v[122:125], v[118:121], v[66:81]
	s_waitcnt lgkmcnt(0)
	v_mfma_f32_32x32x16_bf16 v[66:81], v[126:129], v[114:117], v[66:81]
	ds_read_b128 v[114:117], v204 offset:12288
	ds_read_b128 v[118:121], v205 offset:12288
	ds_read_b128 v[122:125], v206 offset:12288
	ds_read_b128 v[126:129], v207 offset:12288
	s_waitcnt lgkmcnt(3)
	v_mfma_f32_32x32x16_bf16 v[66:81], v[114:117], v[110:113], v[66:81]
	v_exp_f32_e32 v110, v85
	v_exp_f32_e32 v111, v86
	v_exp_f32_e32 v112, v87
	v_exp_f32_e32 v113, v88
	v_exp_f32_e32 v114, v89
	v_exp_f32_e32 v115, v90
	v_exp_f32_e32 v116, v91
	s_waitcnt lgkmcnt(2)
	v_mfma_f32_32x32x16_bf16 v[66:81], v[118:121], v[106:109], v[66:81]
	v_exp_f32_e32 v106, v92
	v_exp_f32_e32 v107, v93
	v_exp_f32_e32 v108, v94
	v_exp_f32_e32 v109, v95
	v_exp_f32_e32 v117, v96
	v_exp_f32_e32 v118, v97
	v_cvt_pk_bf16_f32 v83, v132, v110
	s_waitcnt lgkmcnt(1)
	v_mfma_f32_32x32x16_bf16 v[66:81], v[122:125], v[102:105], v[66:81]
	v_cvt_pk_bf16_f32 v84, v111, v112
	v_cvt_pk_bf16_f32 v85, v113, v114
	v_cvt_pk_bf16_f32 v86, v115, v116
	v_cvt_pk_bf16_f32 v87, v106, v107
	v_cvt_pk_bf16_f32 v88, v108, v109
	v_cvt_pk_bf16_f32 v89, v117, v118
	s_waitcnt lgkmcnt(0)
	v_mfma_f32_32x32x16_bf16 v[66:81], v[126:129], v[98:101], v[66:81]
	ds_read_b64_tr_b16 v[90:91], v208 offset:0
	ds_read_b64_tr_b16 v[92:93], v208 offset:0x800
	ds_read_b64_tr_b16 v[94:95], v208 offset:0x1000
	ds_read_b64_tr_b16 v[96:97], v208 offset:0x1800
	ds_read_b64_tr_b16 v[98:99], v208 offset:0x200
	ds_read_b64_tr_b16 v[100:101], v208 offset:0xa00
	ds_read_b64_tr_b16 v[102:103], v208 offset:0x1200
	ds_read_b64_tr_b16 v[104:105], v208 offset:0x1a00
	s_waitcnt lgkmcnt(4)
	s_nop 0
	v_mfma_f32_32x32x16_bf16 v[2:17], v[82:85], v[90:93], v[2:17]
	s_nop 6
	v_exp_f32_e32 v119, v66
	v_exp_f32_e32 v120, v67
	v_exp_f32_e32 v121, v68
	v_exp_f32_e32 v122, v69
	v_mfma_f32_32x32x16_bf16 v[2:17], v[86:89], v[94:97], v[2:17]
	ds_read_b64_tr_b16 v[66:67], v208 offset:0x400
	ds_read_b64_tr_b16 v[68:69], v208 offset:0xc00
	ds_read_b64_tr_b16 v[90:91], v208 offset:0x1400
	ds_read_b64_tr_b16 v[92:93], v208 offset:0x1c00
	s_waitcnt lgkmcnt(4)
	v_mfma_f32_32x32x16_bf16 v[18:33], v[82:85], v[98:101], v[18:33]
	v_exp_f32_e32 v98, v70
	v_exp_f32_e32 v99, v71
	v_exp_f32_e32 v100, v72
	v_exp_f32_e32 v101, v73
	v_mfma_f32_32x32x16_bf16 v[18:33], v[86:89], v[102:105], v[18:33]
	ds_read_b64_tr_b16 v[70:71], v208 offset:0x600
	ds_read_b64_tr_b16 v[72:73], v208 offset:0xe00
	ds_read_b64_tr_b16 v[94:95], v208 offset:0x1600
	ds_read_b64_tr_b16 v[96:97], v208 offset:0x1e00
	s_waitcnt lgkmcnt(4)
	v_mfma_f32_32x32x16_bf16 v[34:49], v[82:85], v[66:69], v[34:49]
	v_exp_f32_e32 v102, v74
	v_exp_f32_e32 v103, v75
	v_exp_f32_e32 v104, v76
	v_exp_f32_e32 v105, v77
	v_mfma_f32_32x32x16_bf16 v[34:49], v[86:89], v[90:93], v[34:49]
	ds_read_b64_tr_b16 v[74:75], v208 offset:0x2000
	ds_read_b64_tr_b16 v[76:77], v208 offset:0x2800
	ds_read_b64_tr_b16 v[90:91], v208 offset:0x3000
	ds_read_b64_tr_b16 v[92:93], v208 offset:0x3800
	s_waitcnt lgkmcnt(4)
	v_add_f32_e32 v66, v130, v131
	v_add_f32_e32 v67, v119, v120
	v_mfma_f32_32x32x16_bf16 v[50:65], v[82:85], v[70:73], v[50:65]
	v_add_f32_e32 v66, v66, v132
	v_add_f32_e32 v67, v67, v121
	v_exp_f32_e32 v123, v78
	v_add_f32_e32 v66, v66, v110
	v_add_f32_e32 v67, v67, v122
	v_exp_f32_e32 v124, v79
	v_add_f32_e32 v66, v66, v111
	v_add_f32_e32 v67, v67, v98
	v_mfma_f32_32x32x16_bf16 v[50:65], v[86:89], v[94:97], v[50:65]
	v_add_f32_e32 v66, v66, v112
	v_add_f32_e32 v67, v67, v99
	v_exp_f32_e32 v125, v80
	v_add_f32_e32 v66, v66, v113
	v_add_f32_e32 v67, v67, v100
	v_exp_f32_e32 v81, v81
	v_add_f32_e32 v66, v66, v114
	v_add_f32_e32 v67, v67, v101
	v_cvt_pk_bf16_f32 v68, v119, v120
	v_add_f32_e32 v66, v66, v115
	v_add_f32_e32 v67, v67, v102
	v_cvt_pk_bf16_f32 v69, v121, v122
	v_add_f32_e32 v66, v66, v116
	v_add_f32_e32 v67, v67, v103
	v_cvt_pk_bf16_f32 v70, v98, v99
	v_add_f32_e32 v66, v66, v106
	v_add_f32_e32 v67, v67, v104
	v_cvt_pk_bf16_f32 v71, v100, v101
	v_add_f32_e32 v66, v66, v107
	v_add_f32_e32 v67, v67, v105
	v_cvt_pk_bf16_f32 v78, v102, v103
	v_add_f32_e32 v66, v66, v108
	v_add_f32_e32 v67, v67, v123
	v_cvt_pk_bf16_f32 v79, v104, v105
	v_add_f32_e32 v66, v66, v109
	v_add_f32_e32 v67, v67, v124
	v_cvt_pk_bf16_f32 v80, v123, v124
	v_add_f32_e32 v66, v66, v117
	v_add_f32_e32 v67, v67, v125
	v_add_f32_e32 v66, v66, v118
	v_add_f32_e32 v67, v67, v81
	v_cvt_pk_bf16_f32 v81, v125, v81
	v_add_f32_e32 v66, v66, v67
	v_add_f32_e32 v66, v151, v66
	v_mov_b32_e32 v67, v66
	s_nop 1
	v_permlane32_swap_b32_e32 v66, v67
	ds_read_b64_tr_b16 v[82:83], v208 offset:0x2200
	ds_read_b64_tr_b16 v[84:85], v208 offset:0x2a00
	ds_read_b64_tr_b16 v[86:87], v208 offset:0x3200
	ds_read_b64_tr_b16 v[88:89], v208 offset:0x3a00
	s_waitcnt lgkmcnt(4)
	v_mfma_f32_32x32x16_bf16 v[2:17], v[68:71], v[74:77], v[2:17]
	s_nop 0
	v_mfma_f32_32x32x16_bf16 v[2:17], v[78:81], v[90:93], v[2:17]
	ds_read_b64_tr_b16 v[72:73], v208 offset:0x2400
	ds_read_b64_tr_b16 v[74:75], v208 offset:0x2c00
	ds_read_b64_tr_b16 v[90:91], v208 offset:0x3400
	ds_read_b64_tr_b16 v[92:93], v208 offset:0x3c00
	s_waitcnt lgkmcnt(4)
	v_mfma_f32_32x32x16_bf16 v[18:33], v[68:71], v[82:85], v[18:33]
	v_mfma_f32_32x32x16_bf16 v[18:33], v[78:81], v[86:89], v[18:33]
	ds_read_b64_tr_b16 v[82:83], v208 offset:0x2600
	ds_read_b64_tr_b16 v[84:85], v208 offset:0x2e00
	ds_read_b64_tr_b16 v[86:87], v208 offset:0x3600
	ds_read_b64_tr_b16 v[88:89], v208 offset:0x3e00
	s_waitcnt lgkmcnt(4)
	v_mfma_f32_32x32x16_bf16 v[34:49], v[68:71], v[72:75], v[34:49]
	v_mfma_f32_32x32x16_bf16 v[34:49], v[78:81], v[90:93], v[34:49]
	s_waitcnt lgkmcnt(0)
	v_mfma_f32_32x32x16_bf16 v[50:65], v[68:71], v[82:85], v[50:65]
	s_waitcnt vmcnt(0)
	s_barrier
	v_mfma_f32_32x32x16_bf16 v[50:65], v[78:81], v[86:89], v[50:65]
	s_and_saveexec_b64 s[0:1], s[2:3]
	s_cbranch_execz .LBB0_2310
	v_add_f32_e32 v66, v66, v67
	v_lshl_add_u32 v68, v165, 2, s4
	ds_write_b32 v68, v66
	s_branch .LBB0_2310

.LBB0_2318:
	s_lshl_b32 s0, s30, 1
	s_and_b32 s24, s0, 0x700
	s_ashr_i32 s0, s30, 10
	s_ashr_i32 s1, s0, 31
	s_lshl_b64 s[46:47], s[0:1], 14
	s_lshl_b32 s1, s30, 8
	s_and_b32 s1, s1, 0x3f00
	s_or_b32 s46, s46, s1
	s_bfe_u32 s23, s30, 0x40006
	s_mul_i32 s4, s47, 0x3000
	s_mul_hi_u32 s21, s46, 0x3000
	s_lshl_b32 s52, s23, 7
	s_lshl_b32 s1, s0, 8
	s_add_i32 s21, s21, s4
	s_mul_i32 s4, s46, 0x3000
	v_readlane_b32 s40, v242, 17
	v_readlane_b32 s41, v242, 18
	s_add_u32 s4, s40, s4
	s_addc_u32 s21, s41, s21
	s_add_u32 s4, s4, s52
	s_addc_u32 s21, s21, 0
	s_add_u32 s28, s4, 0x1000
	s_addc_u32 s29, s21, 0
	s_mul_i32 s4, s0, 0x300000
	s_mul_hi_i32 s1, s1, 0x3000
	s_add_u32 s4, s40, s4
	s_addc_u32 s21, s41, s1
	s_add_u32 s34, s4, s52
	s_addc_u32 s35, s21, 0
	s_mul_i32 s58, s0, 0xc000000
	s_mul_hi_i32 s25, s0, 0xc000000
	s_add_u32 s0, s40, s58
	s_addc_u32 s1, s41, s25
	s_add_u32 s0, s0, s52
	s_addc_u32 s1, s1, 0
	s_and_b32 s31, s52, 0x700
	s_add_u32 s61, s4, s31
	s_addc_u32 s62, s21, 0
	s_add_u32 s40, s61, 0x18002000
	v_readfirstlane_b32 s33, v0
	s_addc_u32 s41, s62, 0
	s_lshr_b32 s31, s33, 6
	s_lshl_b32 s4, s31, 5
	v_or_b32_e32 v4, s4, v165
	v_mov_b64_e32 v[2:3], s[28:29]
	v_mad_u64_u32 v[2:3], s[28:29], v4, s20, v[2:3]
	v_lshl_add_u64 v[2:3], v[2:3], 0, v[132:133]
	global_load_dwordx4 v[114:117], v[2:3], off
	global_load_dwordx4 v[118:121], v[2:3], off offset:32
	global_load_dwordx4 v[122:125], v[2:3], off offset:64
	global_load_dwordx4 v[126:129], v[2:3], off offset:96
	s_andn2_b32 s33, s33, 63
	s_ashr_i32 s21, s33, 4
	s_and_b32 s28, s21, -16
	s_lshr_b32 s21, s21, 1
	s_and_b32 s21, s21, 4
	v_or_b32_e32 v2, s33, v166
	s_or_b32 s60, s28, s21
	s_add_i32 s21, s33, 0x200
	v_ashrrev_i32_e32 v3, 31, v2
	s_ashr_i32 s21, s21, 4
	v_lshrrev_b32_e32 v3, 29, v3
	s_and_b32 s28, s21, -16
	s_lshr_b32 s21, s21, 1
	v_add_u32_e32 v3, v2, v3
	s_and_b32 s21, s21, 4
	v_ashrrev_i32_e32 v5, 3, v3
	v_and_b32_e32 v3, 0x1ffffff8, v3
	s_or_b32 s59, s28, s21
	v_sub_u32_e32 v3, v2, v3
	v_lshrrev_b32_e32 v4, 1, v5
	v_and_b32_e32 v137, 0x60, v2
	v_or_b32_e32 v2, s60, v163
	v_or_b32_e32 v6, s59, v163
	v_bitop3_b32 v3, v4, v3, 7 bitop3:0x6c
	v_or_b32_e32 v4, v137, v162
	v_lshrrev_b32_e32 v7, 1, v2
	v_xor_b32_e32 v7, v7, v2
	v_and_b32_e32 v7, 4, v7
	v_lshl_or_b32 v7, v7, 1, v7
	v_xor_b32_e32 v2, v2, v7
	v_lshrrev_b32_e32 v7, 1, v6
	v_xor_b32_e32 v7, v7, v6
	v_and_b32_e32 v7, 4, v7
	v_lshl_or_b32 v7, v7, 1, v7
	v_xor_b32_e32 v6, v6, v7
	v_mul_lo_u32 v2, v2, s22
	v_mul_lo_u32 v6, v6, s22
	v_mul_lo_u32 v5, v5, s22
	v_or_b32_e32 v2, v2, v4
	v_or_b32_e32 v4, v6, v4
	v_lshl_add_u32 v6, v3, 3, v5
	v_ashrrev_i32_e32 v7, 31, v6
	v_lshlrev_b64 v[150:151], 1, v[6:7]
	s_lshl_b32 s21, s31, 10
	v_lshl_add_u64 v[98:99], s[34:35], 0, v[150:151]
	s_add_i32 s34, s21, 0
	s_add_i32 s35, s34, 0x8000
	v_ashrrev_i32_e32 v3, 31, v2
	v_lshl_add_u64 v[6:7], v[98:99], 0, s[6:7]
	s_mov_b32 m0, s35
	v_lshlrev_b64 v[152:153], 1, v[2:3]
	v_ashrrev_i32_e32 v5, 31, v4
	global_load_lds_dwordx4 v[6:7], off
	v_lshl_add_u64 v[2:3], s[40:41], 0, v[152:153]
	s_mov_b32 m0, s34
	v_lshlrev_b64 v[154:155], 1, v[4:5]
	s_add_i32 s54, s34, 0x2000
	global_load_lds_dwordx4 v[2:3], off
	v_lshl_add_u64 v[2:3], s[40:41], 0, v[154:155]
	s_mov_b32 m0, s54
	s_add_i32 s55, s34, 0xa000
	global_load_lds_dwordx4 v[2:3], off
	v_lshl_add_u64 v[2:3], v[98:99], 0, s[8:9]
	s_mov_b32 m0, s55
	s_waitcnt vmcnt(0)
	s_waitcnt vmcnt(0) lgkmcnt(0)
	s_barrier
	global_load_lds_dwordx4 v[2:3], off
	ds_read_b128 v[2:5], v172 offset:32768
	ds_read_b128 v[18:21], v172 offset:36864
	s_waitcnt lgkmcnt(0)
	v_mfma_f32_32x32x16_bf16 v[2:17], v[2:5], v[114:117], 0
	ds_read_b128 v[22:25], v173 offset:32768
	ds_read_b128 v[34:37], v173 offset:36864
	s_add_u32 s28, s61, 0x180c2000
	v_lshl_add_u64 v[30:31], v[98:99], 0, s[12:13]
	s_mov_b32 m0, s35
	s_addc_u32 s29, s62, 0
	s_add_i32 s56, s34, 0x4000
	s_add_i32 s57, s34, 0x6000
	s_waitcnt lgkmcnt(0)
	v_mfma_f32_32x32x16_bf16 v[2:17], v[22:25], v[118:121], v[2:17]
	ds_read_b128 v[22:25], v174 offset:32768
	ds_read_b128 v[38:41], v174 offset:36864
	ds_read_b128 v[26:29], v175 offset:32768
	ds_read_b128 v[42:45], v175 offset:36864
	s_waitcnt vmcnt(0)
	s_waitcnt vmcnt(0) lgkmcnt(0)
	s_barrier
	global_load_lds_dwordx4 v[30:31], off
	v_mfma_f32_32x32x16_bf16 v[2:17], v[22:25], v[122:125], v[2:17]
	v_lshl_add_u64 v[22:23], s[28:29], 0, v[152:153]
	s_mov_b32 m0, s56
	s_mov_b32 s53, s5
	global_load_lds_dwordx4 v[22:23], off
	v_lshl_add_u64 v[22:23], s[28:29], 0, v[154:155]
	s_mov_b32 m0, s57
	v_mfma_f32_32x32x16_bf16 v[2:17], v[26:29], v[126:129], v[2:17]
	global_load_lds_dwordx4 v[22:23], off
	v_mfma_f32_32x32x16_bf16 v[18:33], v[18:21], v[114:117], 0
	s_nop 9
	v_exp_f32_e32 v54, v2
	v_exp_f32_e32 v55, v3
	v_exp_f32_e32 v56, v4
	v_exp_f32_e32 v57, v5
	v_exp_f32_e32 v58, v6
	v_exp_f32_e32 v59, v7
	v_exp_f32_e32 v60, v8
	v_mfma_f32_32x32x16_bf16 v[18:33], v[34:37], v[118:121], v[18:33]
	v_exp_f32_e32 v61, v9
	v_exp_f32_e32 v62, v10
	v_exp_f32_e32 v63, v11
	v_exp_f32_e32 v64, v12
	v_exp_f32_e32 v65, v13
	v_exp_f32_e32 v102, v14
	v_exp_f32_e32 v103, v15
	v_mfma_f32_32x32x16_bf16 v[18:33], v[38:41], v[122:125], v[18:33]
	v_exp_f32_e32 v104, v16
	v_exp_f32_e32 v105, v17
	ds_read_b128 v[2:5], v172 offset:40960
	ds_read_b128 v[6:9], v172 offset:45056
	ds_read_b128 v[10:13], v173 offset:40960
	ds_read_b128 v[14:17], v173 offset:45056
	ds_read_b128 v[34:37], v174 offset:40960
	ds_read_b128 v[38:41], v174 offset:45056
	ds_read_b128 v[46:49], v175 offset:40960
	ds_read_b128 v[50:53], v175 offset:45056
	v_mfma_f32_32x32x16_bf16 v[18:33], v[42:45], v[126:129], v[18:33]
	s_waitcnt lgkmcnt(0)
	v_mfma_f32_32x32x16_bf16 v[66:81], v[6:9], v[114:117], 0
	v_mfma_f32_32x32x16_bf16 v[82:97], v[2:5], v[114:117], 0
	s_nop 8
	v_exp_f32_e32 v2, v18
	v_exp_f32_e32 v3, v19
	v_exp_f32_e32 v4, v20
	v_exp_f32_e32 v5, v21
	v_exp_f32_e32 v18, v22
	v_exp_f32_e32 v19, v23
	v_exp_f32_e32 v20, v24
	v_exp_f32_e32 v21, v25
	v_mfma_f32_32x32x16_bf16 v[66:81], v[14:17], v[118:121], v[66:81]
	v_exp_f32_e32 v6, v26
	v_exp_f32_e32 v7, v27
	v_exp_f32_e32 v8, v28
	v_exp_f32_e32 v9, v29
	v_mfma_f32_32x32x16_bf16 v[82:97], v[10:13], v[118:121], v[82:97]
	v_exp_f32_e32 v10, v30
	v_exp_f32_e32 v11, v31
	v_exp_f32_e32 v12, v32
	v_exp_f32_e32 v13, v33
	v_add_f32_e32 v14, v54, v55
	v_add_f32_e32 v15, v2, v3
	v_mfma_f32_32x32x16_bf16 v[66:81], v[38:41], v[122:125], v[66:81]
	v_add_f32_e32 v14, v14, v56
	v_add_f32_e32 v15, v15, v4
	v_cvt_pk_bf16_f32 v54, v54, v55
	v_add_f32_e32 v14, v14, v57
	v_add_f32_e32 v15, v15, v5
	v_cvt_pk_bf16_f32 v55, v56, v57
	v_add_f32_e32 v14, v14, v58
	v_add_f32_e32 v15, v15, v18
	v_cvt_pk_bf16_f32 v56, v58, v59
	v_add_f32_e32 v14, v14, v59
	v_add_f32_e32 v15, v15, v19
	v_cvt_pk_bf16_f32 v57, v60, v61
	v_add_f32_e32 v14, v14, v60
	v_add_f32_e32 v15, v15, v20
	s_nop 0
	v_add_f32_e32 v14, v14, v61
	v_add_f32_e32 v15, v15, v21
	v_add_f32_e32 v14, v14, v62
	v_add_f32_e32 v15, v15, v6
	v_mfma_f32_32x32x16_bf16 v[82:97], v[34:37], v[122:125], v[82:97]
	v_add_f32_e32 v14, v14, v63
	v_add_f32_e32 v15, v15, v7
	s_nop 0
	v_add_f32_e32 v14, v14, v64
	v_add_f32_e32 v15, v15, v8
	s_nop 0
	v_add_f32_e32 v14, v14, v65
	v_add_f32_e32 v15, v15, v9
	s_nop 0
	v_add_f32_e32 v14, v14, v102
	v_add_f32_e32 v15, v15, v10
	s_nop 0
	v_add_f32_e32 v14, v14, v103
	v_add_f32_e32 v15, v15, v11
	s_nop 0
	v_add_f32_e32 v14, v14, v104
	v_add_f32_e32 v15, v15, v12
	s_nop 0
	v_add_f32_e32 v14, v14, v105
	v_add_f32_e32 v15, v15, v13
	s_nop 0
	v_add_f32_e32 v14, v14, v15
	v_mov_b32_e32 v15, v14
	s_nop 1
	v_permlane32_swap_b32_e32 v14, v15
	v_add_f32_e32 v14, v14, v15
	v_add_f32_e32 v135, 0, v14
	v_mfma_f32_32x32x16_bf16 v[66:81], v[50:53], v[126:129], v[66:81]
	v_cvt_pk_bf16_f32 v100, v62, v63
	v_cvt_pk_bf16_f32 v101, v64, v65
	v_cvt_pk_bf16_f32 v102, v102, v103
	v_cvt_pk_bf16_f32 v103, v104, v105
	v_cvt_pk_bf16_f32 v104, v2, v3
	v_cvt_pk_bf16_f32 v105, v4, v5
	v_cvt_pk_bf16_f32 v106, v18, v19
	v_cvt_pk_bf16_f32 v107, v20, v21
	v_cvt_pk_bf16_f32 v108, v6, v7
	v_cvt_pk_bf16_f32 v109, v8, v9
	v_cvt_pk_bf16_f32 v110, v10, v11
	v_cvt_pk_bf16_f32 v111, v12, v13
	v_mfma_f32_32x32x16_bf16 v[82:97], v[46:49], v[126:129], v[82:97]
	ds_read_b64_tr_b16 v[2:3], v168 offset:0
	ds_read_b64_tr_b16 v[4:5], v168 offset:0x800
	ds_read_b64_tr_b16 v[18:19], v168 offset:0x1000
	ds_read_b64_tr_b16 v[20:21], v168 offset:0x1800
	ds_read_b64_tr_b16 v[22:23], v168 offset:0x2000
	ds_read_b64_tr_b16 v[24:25], v168 offset:0x2800
	ds_read_b64_tr_b16 v[26:27], v168 offset:0x3000
	ds_read_b64_tr_b16 v[28:29], v168 offset:0x3800
	ds_read_b64_tr_b16 v[30:31], v168 offset:0x200
	ds_read_b64_tr_b16 v[32:33], v168 offset:0xa00
	ds_read_b64_tr_b16 v[34:35], v168 offset:0x1200
	ds_read_b64_tr_b16 v[36:37], v168 offset:0x1a00
	ds_read_b64_tr_b16 v[38:39], v168 offset:0x2200
	ds_read_b64_tr_b16 v[40:41], v168 offset:0x2a00
	ds_read_b64_tr_b16 v[42:43], v168 offset:0x3200
	ds_read_b64_tr_b16 v[44:45], v168 offset:0x3a00
	s_waitcnt lgkmcnt(8)
	s_nop 0
	v_mfma_f32_32x32x16_bf16 v[2:17], v[54:57], v[2:5], 0
	s_nop 3
	v_exp_f32_e32 v139, v82
	v_exp_f32_e32 v141, v83
	v_exp_f32_e32 v143, v84
	v_exp_f32_e32 v145, v85
	v_mfma_f32_32x32x16_bf16 v[2:17], v[100:103], v[18:21], v[2:17]
	v_mfma_f32_32x32x16_bf16 v[2:17], v[104:107], v[22:25], v[2:17]
	v_mfma_f32_32x32x16_bf16 v[2:17], v[108:111], v[26:29], v[2:17]
	ds_read_b64_tr_b16 v[46:47], v168 offset:0x400
	ds_read_b64_tr_b16 v[48:49], v168 offset:0xc00
	ds_read_b64_tr_b16 v[50:51], v168 offset:0x1400
	ds_read_b64_tr_b16 v[52:53], v168 offset:0x1c00
	ds_read_b64_tr_b16 v[58:59], v168 offset:0x2400
	ds_read_b64_tr_b16 v[60:61], v168 offset:0x2c00
	ds_read_b64_tr_b16 v[62:63], v168 offset:0x3400
	ds_read_b64_tr_b16 v[64:65], v168 offset:0x3c00
	s_waitcnt lgkmcnt(8)
	v_mfma_f32_32x32x16_bf16 v[18:33], v[54:57], v[30:33], 0
	v_exp_f32_e32 v147, v86
	v_exp_f32_e32 v149, v87
	v_exp_f32_e32 v196, v88
	v_exp_f32_e32 v197, v89
	v_mfma_f32_32x32x16_bf16 v[18:33], v[100:103], v[34:37], v[18:33]
	v_mfma_f32_32x32x16_bf16 v[18:33], v[104:107], v[38:41], v[18:33]
	v_mfma_f32_32x32x16_bf16 v[18:33], v[108:111], v[42:45], v[18:33]
	ds_read_b64_tr_b16 v[82:83], v168 offset:0x600
	ds_read_b64_tr_b16 v[84:85], v168 offset:0xe00
	ds_read_b64_tr_b16 v[86:87], v168 offset:0x1600
	ds_read_b64_tr_b16 v[88:89], v168 offset:0x1e00
	ds_read_b64_tr_b16 v[156:157], v168 offset:0x2600
	ds_read_b64_tr_b16 v[158:159], v168 offset:0x2e00
	ds_read_b64_tr_b16 v[176:177], v168 offset:0x3600
	ds_read_b64_tr_b16 v[178:179], v168 offset:0x3e00
	s_waitcnt lgkmcnt(8)
	v_mfma_f32_32x32x16_bf16 v[34:49], v[54:57], v[46:49], 0
	v_exp_f32_e32 v198, v90
	v_exp_f32_e32 v199, v91
	v_exp_f32_e32 v200, v92
	v_exp_f32_e32 v201, v93
	v_mfma_f32_32x32x16_bf16 v[34:49], v[100:103], v[50:53], v[34:49]
	v_mfma_f32_32x32x16_bf16 v[34:49], v[104:107], v[58:61], v[34:49]
	v_mfma_f32_32x32x16_bf16 v[34:49], v[108:111], v[62:65], v[34:49]
	s_waitcnt lgkmcnt(0)
	v_mfma_f32_32x32x16_bf16 v[50:65], v[54:57], v[82:85], 0
	v_exp_f32_e32 v202, v94
	v_exp_f32_e32 v203, v95
	v_exp_f32_e32 v204, v96
	v_exp_f32_e32 v205, v97
	v_mfma_f32_32x32x16_bf16 v[50:65], v[100:103], v[86:89], v[50:65]
	v_mfma_f32_32x32x16_bf16 v[50:65], v[104:107], v[156:159], v[50:65]
	v_mfma_f32_32x32x16_bf16 v[50:65], v[108:111], v[176:179], v[50:65]
	s_add_u32 s28, s61, 0x18182000
	s_mov_b32 m0, s55
	v_lshl_add_u64 v[82:83], v[98:99], 0, s[16:17]
	s_addc_u32 s29, s62, 0
	s_waitcnt vmcnt(0)
	s_waitcnt vmcnt(0)
	s_barrier
	global_load_lds_dwordx4 v[82:83], off
	v_lshl_add_u64 v[82:83], s[28:29], 0, v[152:153]
	s_mov_b32 m0, s34
	v_lshl_add_u64 v[90:91], s[0:1], 0, v[150:151]
	global_load_lds_dwordx4 v[82:83], off
	v_lshl_add_u64 v[82:83], s[28:29], 0, v[154:155]
	s_mov_b32 m0, s54
	v_lshl_add_u64 v[160:161], v[90:91], 0, s[14:15]
	global_load_lds_dwordx4 v[82:83], off
	ds_read_b128 v[82:85], v172 offset:32768
	ds_read_b128 v[86:89], v172 offset:36864
	ds_read_b128 v[156:159], v173 offset:32768
	ds_read_b128 v[176:179], v173 offset:36864
	ds_read_b128 v[180:183], v174 offset:32768
	ds_read_b128 v[184:187], v174 offset:36864
	ds_read_b128 v[188:191], v175 offset:32768
	ds_read_b128 v[192:195], v175 offset:36864
	s_waitcnt lgkmcnt(0)
	v_mfma_f32_32x32x16_bf16 v[98:113], v[82:85], v[114:117], 0
	v_exp_f32_e32 v206, v66
	v_exp_f32_e32 v207, v67
	v_exp_f32_e32 v208, v68
	v_exp_f32_e32 v209, v69
	v_exp_f32_e32 v210, v70
	v_exp_f32_e32 v211, v71
	v_exp_f32_e32 v212, v72
	v_exp_f32_e32 v213, v73
	v_mfma_f32_32x32x16_bf16 v[82:97], v[86:89], v[114:117], 0
	v_exp_f32_e32 v81, v81
	v_mfma_f32_32x32x16_bf16 v[98:113], v[156:159], v[118:121], v[98:113]
	v_exp_f32_e32 v157, v74
	v_exp_f32_e32 v159, v75
	v_exp_f32_e32 v214, v76
	v_exp_f32_e32 v215, v77
	v_exp_f32_e32 v216, v78
	v_exp_f32_e32 v217, v79
	v_exp_f32_e32 v218, v80
	v_mfma_f32_32x32x16_bf16 v[82:97], v[176:179], v[118:121], v[82:97]
	v_add_f32_e32 v66, v139, v141
	v_add_f32_e32 v67, v206, v207
	v_cvt_pk_bf16_f32 v68, v147, v149
	v_add_f32_e32 v66, v66, v143
	v_add_f32_e32 v67, v67, v208
	v_cvt_pk_bf16_f32 v69, v196, v197
	v_add_f32_e32 v66, v66, v145
	v_add_f32_e32 v67, v67, v209
	v_mfma_f32_32x32x16_bf16 v[98:113], v[180:183], v[122:125], v[98:113]
	v_add_f32_e32 v66, v66, v147
	v_add_f32_e32 v67, v67, v210
	s_nop 0
	v_add_f32_e32 v66, v66, v149
	v_add_f32_e32 v67, v67, v211
	s_nop 0
	v_add_f32_e32 v66, v66, v196
	v_add_f32_e32 v67, v67, v212
	v_mfma_f32_32x32x16_bf16 v[82:97], v[184:187], v[122:125], v[82:97]
	v_add_f32_e32 v66, v66, v197
	v_add_f32_e32 v67, v67, v213
	s_nop 0
	v_add_f32_e32 v66, v66, v198
	v_add_f32_e32 v67, v67, v157
	s_nop 0
	v_add_f32_e32 v66, v66, v199
	v_add_f32_e32 v67, v67, v159
	s_nop 0
	v_add_f32_e32 v66, v66, v200
	v_add_f32_e32 v67, v67, v214
	s_nop 0
	v_add_f32_e32 v66, v66, v201
	v_add_f32_e32 v67, v67, v215
	s_nop 0
	v_add_f32_e32 v66, v66, v202
	v_add_f32_e32 v67, v67, v216
	s_nop 0
	v_add_f32_e32 v66, v66, v203
	v_add_f32_e32 v67, v67, v217
	s_nop 0
	v_add_f32_e32 v66, v66, v204
	v_add_f32_e32 v67, v67, v218
	s_nop 0
	v_add_f32_e32 v66, v66, v205
	v_add_f32_e32 v67, v67, v81
	s_nop 0
	v_add_f32_e32 v156, v66, v67
	v_cvt_pk_bf16_f32 v66, v139, v141
	v_cvt_pk_bf16_f32 v67, v143, v145
	v_mov_b32_e32 v158, v156
	v_permlane32_swap_b32_e32 v156, v158
	v_cvt_pk_bf16_f32 v70, v198, v199
	v_cvt_pk_bf16_f32 v71, v200, v201
	v_cvt_pk_bf16_f32 v72, v202, v203
	v_cvt_pk_bf16_f32 v73, v204, v205
	v_cvt_pk_bf16_f32 v74, v206, v207
	v_cvt_pk_bf16_f32 v75, v208, v209
	v_cvt_pk_bf16_f32 v76, v210, v211
	v_cvt_pk_bf16_f32 v77, v212, v213
	v_cvt_pk_bf16_f32 v78, v157, v159
	v_cvt_pk_bf16_f32 v79, v214, v215
	v_cvt_pk_bf16_f32 v80, v216, v217
	v_cvt_pk_bf16_f32 v81, v218, v81
	v_mfma_f32_32x32x16_bf16 v[98:113], v[188:191], v[126:129], v[98:113]
	v_mfma_f32_32x32x16_bf16 v[82:97], v[192:195], v[126:129], v[82:97]
	ds_read_b64_tr_b16 v[176:177], v169 offset:0
	ds_read_b64_tr_b16 v[178:179], v169 offset:0x800
	ds_read_b64_tr_b16 v[180:181], v169 offset:0x1000
	ds_read_b64_tr_b16 v[182:183], v169 offset:0x1800
	ds_read_b64_tr_b16 v[184:185], v169 offset:0x2000
	ds_read_b64_tr_b16 v[186:187], v169 offset:0x2800
	ds_read_b64_tr_b16 v[188:189], v169 offset:0x3000
	ds_read_b64_tr_b16 v[190:191], v169 offset:0x3800
	ds_read_b64_tr_b16 v[192:193], v169 offset:0x200
	ds_read_b64_tr_b16 v[194:195], v169 offset:0xa00
	ds_read_b64_tr_b16 v[196:197], v169 offset:0x1200
	ds_read_b64_tr_b16 v[198:199], v169 offset:0x1a00
	ds_read_b64_tr_b16 v[200:201], v169 offset:0x2200
	ds_read_b64_tr_b16 v[202:203], v169 offset:0x2a00
	ds_read_b64_tr_b16 v[204:205], v169 offset:0x3200
	ds_read_b64_tr_b16 v[206:207], v169 offset:0x3a00
	s_waitcnt lgkmcnt(8)
	s_nop 0
	v_mfma_f32_32x32x16_bf16 v[2:17], v[66:69], v[176:179], v[2:17]
	s_nop 8
	v_exp_f32_e32 v139, v98
	v_exp_f32_e32 v141, v99
	v_exp_f32_e32 v143, v100
	v_exp_f32_e32 v145, v101
	v_mfma_f32_32x32x16_bf16 v[2:17], v[70:73], v[180:183], v[2:17]
	v_mfma_f32_32x32x16_bf16 v[2:17], v[74:77], v[184:187], v[2:17]
	v_mfma_f32_32x32x16_bf16 v[2:17], v[78:81], v[188:191], v[2:17]
	ds_read_b64_tr_b16 v[98:99], v169 offset:0x400
	ds_read_b64_tr_b16 v[100:101], v169 offset:0xc00
	ds_read_b64_tr_b16 v[176:177], v169 offset:0x1400
	ds_read_b64_tr_b16 v[178:179], v169 offset:0x1c00
	ds_read_b64_tr_b16 v[180:181], v169 offset:0x2400
	ds_read_b64_tr_b16 v[182:183], v169 offset:0x2c00
	ds_read_b64_tr_b16 v[184:185], v169 offset:0x3400
	ds_read_b64_tr_b16 v[186:187], v169 offset:0x3c00
	s_waitcnt lgkmcnt(8)
	v_mfma_f32_32x32x16_bf16 v[18:33], v[66:69], v[192:195], v[18:33]
	v_exp_f32_e32 v147, v102
	v_exp_f32_e32 v149, v103
	v_mfma_f32_32x32x16_bf16 v[18:33], v[70:73], v[196:199], v[18:33]
	v_mfma_f32_32x32x16_bf16 v[18:33], v[74:77], v[200:203], v[18:33]
	v_exp_f32_e32 v200, v104
	v_exp_f32_e32 v201, v105
	v_mfma_f32_32x32x16_bf16 v[18:33], v[78:81], v[204:207], v[18:33]
	ds_read_b64_tr_b16 v[102:103], v169 offset:0x600
	ds_read_b64_tr_b16 v[104:105], v169 offset:0xe00
	ds_read_b64_tr_b16 v[188:189], v169 offset:0x1600
	ds_read_b64_tr_b16 v[190:191], v169 offset:0x1e00
	ds_read_b64_tr_b16 v[192:193], v169 offset:0x2600
	ds_read_b64_tr_b16 v[194:195], v169 offset:0x2e00
	ds_read_b64_tr_b16 v[196:197], v169 offset:0x3600
	ds_read_b64_tr_b16 v[198:199], v169 offset:0x3e00
	s_waitcnt lgkmcnt(8)
	v_mfma_f32_32x32x16_bf16 v[34:49], v[66:69], v[98:101], v[34:49]
	v_exp_f32_e32 v202, v106
	v_exp_f32_e32 v203, v107
	v_exp_f32_e32 v204, v108
	v_exp_f32_e32 v205, v109
	v_mfma_f32_32x32x16_bf16 v[34:49], v[70:73], v[176:179], v[34:49]
	v_mfma_f32_32x32x16_bf16 v[34:49], v[74:77], v[180:183], v[34:49]
	v_mfma_f32_32x32x16_bf16 v[34:49], v[78:81], v[184:187], v[34:49]
	s_waitcnt lgkmcnt(0)
	v_mfma_f32_32x32x16_bf16 v[50:65], v[66:69], v[102:105], v[50:65]
	v_exp_f32_e32 v206, v110
	v_exp_f32_e32 v207, v111
	v_exp_f32_e32 v208, v112
	v_exp_f32_e32 v209, v113
	v_mfma_f32_32x32x16_bf16 v[50:65], v[70:73], v[188:191], v[50:65]
	v_mfma_f32_32x32x16_bf16 v[50:65], v[74:77], v[192:195], v[50:65]
	v_mfma_f32_32x32x16_bf16 v[50:65], v[78:81], v[196:199], v[50:65]
	s_add_u32 s0, s61, 0x18242000
	s_mov_b32 m0, s35
	s_addc_u32 s1, s62, 0
	s_waitcnt vmcnt(0)
	s_waitcnt vmcnt(0)
	s_barrier
	global_load_lds_dwordx4 v[160:161], off
	v_lshl_add_u64 v[66:67], s[0:1], 0, v[152:153]
	s_mov_b32 m0, s56
	s_nop 0
	global_load_lds_dwordx4 v[66:67], off
	v_lshl_add_u64 v[66:67], s[0:1], 0, v[154:155]
	s_mov_b32 m0, s57
	s_nop 0
	global_load_lds_dwordx4 v[66:67], off
	ds_read_b128 v[66:69], v172 offset:40960
	ds_read_b128 v[70:73], v172 offset:45056
	ds_read_b128 v[152:155], v173 offset:40960
	ds_read_b128 v[176:179], v173 offset:45056
	ds_read_b128 v[180:183], v174 offset:40960
	ds_read_b128 v[184:187], v174 offset:45056
	ds_read_b128 v[188:191], v175 offset:40960
	ds_read_b128 v[192:195], v175 offset:45056
	s_waitcnt lgkmcnt(0)
	v_mfma_f32_32x32x16_bf16 v[98:113], v[66:69], v[114:117], 0
	v_exp_f32_e32 v160, v82
	v_exp_f32_e32 v161, v83
	v_exp_f32_e32 v196, v84
	v_exp_f32_e32 v197, v85
	v_exp_f32_e32 v198, v86
	v_exp_f32_e32 v199, v87
	v_exp_f32_e32 v210, v88
	v_mfma_f32_32x32x16_bf16 v[66:81], v[70:73], v[114:117], 0
	v_exp_f32_e32 v211, v89
	v_mfma_f32_32x32x16_bf16 v[66:81], v[176:179], v[118:121], v[66:81]
	v_exp_f32_e32 v212, v94
	v_exp_f32_e32 v213, v95
	v_exp_f32_e32 v214, v96
	v_exp_f32_e32 v97, v97
	v_mfma_f32_32x32x16_bf16 v[98:113], v[152:155], v[118:121], v[98:113]
	v_exp_f32_e32 v152, v90
	v_exp_f32_e32 v153, v91
	v_exp_f32_e32 v154, v92
	v_exp_f32_e32 v155, v93
	v_add_f32_e32 v82, v139, v141
	v_add_f32_e32 v83, v160, v161
	v_mfma_f32_32x32x16_bf16 v[66:81], v[184:187], v[122:125], v[66:81]
	v_add_f32_e32 v82, v82, v143
	v_add_f32_e32 v83, v83, v196
	v_cvt_pk_bf16_f32 v84, v147, v149
	v_add_f32_e32 v82, v82, v145
	v_add_f32_e32 v83, v83, v197
	v_cvt_pk_bf16_f32 v85, v200, v201
	v_add_f32_e32 v82, v82, v147
	v_add_f32_e32 v83, v83, v198
	v_mfma_f32_32x32x16_bf16 v[98:113], v[180:183], v[122:125], v[98:113]
	v_add_f32_e32 v82, v82, v149
	v_add_f32_e32 v83, v83, v199
	s_nop 0
	v_add_f32_e32 v82, v82, v200
	v_add_f32_e32 v83, v83, v210
	s_nop 0
	v_add_f32_e32 v82, v82, v201
	v_add_f32_e32 v83, v83, v211
	s_nop 0
	v_add_f32_e32 v82, v82, v202
	v_add_f32_e32 v83, v83, v152
	s_nop 0
	v_add_f32_e32 v82, v82, v203
	v_add_f32_e32 v83, v83, v153
	s_nop 0
	v_add_f32_e32 v82, v82, v204
	v_add_f32_e32 v83, v83, v154
	s_nop 0
	v_add_f32_e32 v82, v82, v205
	v_add_f32_e32 v83, v83, v155
	s_nop 0
	v_add_f32_e32 v82, v82, v206
	v_add_f32_e32 v83, v83, v212
	s_nop 0
	v_add_f32_e32 v82, v82, v207
	v_add_f32_e32 v83, v83, v213
	s_nop 0
	v_add_f32_e32 v82, v82, v208
	v_add_f32_e32 v83, v83, v214
	s_nop 0
	v_add_f32_e32 v82, v82, v209
	v_add_f32_e32 v83, v83, v97
	s_nop 0
	v_add_f32_e32 v157, v82, v83
	v_mov_b32_e32 v159, v157
	s_nop 1
	v_permlane32_swap_b32_e32 v157, v159
	v_add_f32_e64 v82, v156, v158
	v_add_f32_e64 v83, v157, v159
	v_add_f32_e32 v82, v135, v82
	v_add_f32_e32 v135, v82, v83
	v_cvt_pk_bf16_f32 v82, v139, v141
	v_cvt_pk_bf16_f32 v83, v143, v145
	v_mfma_f32_32x32x16_bf16 v[66:81], v[192:195], v[126:129], v[66:81]
	v_cvt_pk_bf16_f32 v86, v202, v203
	v_cvt_pk_bf16_f32 v87, v204, v205
	v_cvt_pk_bf16_f32 v88, v206, v207
	v_cvt_pk_bf16_f32 v89, v208, v209
	v_cvt_pk_bf16_f32 v90, v160, v161
	v_cvt_pk_bf16_f32 v91, v196, v197
	v_cvt_pk_bf16_f32 v92, v198, v199
	v_cvt_pk_bf16_f32 v93, v210, v211
	v_cvt_pk_bf16_f32 v94, v152, v153
	v_cvt_pk_bf16_f32 v95, v154, v155
	v_cvt_pk_bf16_f32 v96, v212, v213
	v_cvt_pk_bf16_f32 v97, v214, v97
	v_mfma_f32_32x32x16_bf16 v[98:113], v[188:191], v[126:129], v[98:113]
	ds_read_b64_tr_b16 v[152:153], v168 offset:0
	ds_read_b64_tr_b16 v[154:155], v168 offset:0x800
	ds_read_b64_tr_b16 v[156:157], v168 offset:0x1000
	ds_read_b64_tr_b16 v[158:159], v168 offset:0x1800
	ds_read_b64_tr_b16 v[176:177], v168 offset:0x2000
	ds_read_b64_tr_b16 v[178:179], v168 offset:0x2800
	ds_read_b64_tr_b16 v[180:181], v168 offset:0x3000
	ds_read_b64_tr_b16 v[182:183], v168 offset:0x3800
	ds_read_b64_tr_b16 v[184:185], v168 offset:0x200
	ds_read_b64_tr_b16 v[186:187], v168 offset:0xa00
	ds_read_b64_tr_b16 v[188:189], v168 offset:0x1200
	ds_read_b64_tr_b16 v[190:191], v168 offset:0x1a00
	ds_read_b64_tr_b16 v[192:193], v168 offset:0x2200
	ds_read_b64_tr_b16 v[194:195], v168 offset:0x2a00
	ds_read_b64_tr_b16 v[196:197], v168 offset:0x3200
	ds_read_b64_tr_b16 v[198:199], v168 offset:0x3a00
	s_waitcnt lgkmcnt(8)
	s_nop 0
	v_mfma_f32_32x32x16_bf16 v[2:17], v[82:85], v[152:155], v[2:17]
	s_nop 3
	v_exp_f32_e32 v139, v98
	v_exp_f32_e32 v141, v99
	v_exp_f32_e32 v143, v100
	v_exp_f32_e32 v145, v101
	v_mfma_f32_32x32x16_bf16 v[2:17], v[86:89], v[156:159], v[2:17]
	v_mfma_f32_32x32x16_bf16 v[2:17], v[90:93], v[176:179], v[2:17]
	v_mfma_f32_32x32x16_bf16 v[2:17], v[94:97], v[180:183], v[2:17]
	ds_read_b64_tr_b16 v[98:99], v168 offset:0x400
	ds_read_b64_tr_b16 v[100:101], v168 offset:0xc00
	ds_read_b64_tr_b16 v[152:153], v168 offset:0x1400
	ds_read_b64_tr_b16 v[154:155], v168 offset:0x1c00
	ds_read_b64_tr_b16 v[156:157], v168 offset:0x2400
	ds_read_b64_tr_b16 v[158:159], v168 offset:0x2c00
	ds_read_b64_tr_b16 v[200:201], v168 offset:0x3400
	ds_read_b64_tr_b16 v[202:203], v168 offset:0x3c00
	s_waitcnt lgkmcnt(8)
	v_mfma_f32_32x32x16_bf16 v[18:33], v[82:85], v[184:187], v[18:33]
	v_exp_f32_e32 v147, v102
	v_exp_f32_e32 v149, v103
	v_exp_f32_e32 v176, v104
	v_exp_f32_e32 v177, v105
	v_mfma_f32_32x32x16_bf16 v[18:33], v[86:89], v[188:191], v[18:33]
	v_mfma_f32_32x32x16_bf16 v[18:33], v[90:93], v[192:195], v[18:33]
	v_mfma_f32_32x32x16_bf16 v[18:33], v[94:97], v[196:199], v[18:33]
	ds_read_b64_tr_b16 v[102:103], v168 offset:0x600
	ds_read_b64_tr_b16 v[104:105], v168 offset:0xe00
	ds_read_b64_tr_b16 v[182:183], v168 offset:0x1600
	ds_read_b64_tr_b16 v[184:185], v168 offset:0x1e00
	ds_read_b64_tr_b16 v[186:187], v168 offset:0x2600
	ds_read_b64_tr_b16 v[188:189], v168 offset:0x2e00
	ds_read_b64_tr_b16 v[190:191], v168 offset:0x3600
	ds_read_b64_tr_b16 v[192:193], v168 offset:0x3e00
	s_waitcnt lgkmcnt(8)
	v_mfma_f32_32x32x16_bf16 v[34:49], v[82:85], v[98:101], v[34:49]
	v_exp_f32_e32 v178, v106
	v_exp_f32_e32 v179, v107
	v_exp_f32_e32 v180, v108
	v_exp_f32_e32 v181, v109
	v_mfma_f32_32x32x16_bf16 v[34:49], v[86:89], v[152:155], v[34:49]
	v_mfma_f32_32x32x16_bf16 v[34:49], v[90:93], v[156:159], v[34:49]
	v_mfma_f32_32x32x16_bf16 v[34:49], v[94:97], v[200:203], v[34:49]
	s_waitcnt lgkmcnt(0)
	v_mfma_f32_32x32x16_bf16 v[50:65], v[82:85], v[102:105], v[50:65]
	v_mfma_f32_32x32x16_bf16 v[50:65], v[86:89], v[182:185], v[50:65]
	v_exp_f32_e32 v182, v110
	v_exp_f32_e32 v183, v111
	v_exp_f32_e32 v184, v112
	v_exp_f32_e32 v185, v113
	v_mfma_f32_32x32x16_bf16 v[50:65], v[90:93], v[186:189], v[50:65]
	v_mfma_f32_32x32x16_bf16 v[50:65], v[94:97], v[190:193], v[50:65]
	v_add_u32_e32 v82, s60, v163
	v_lshrrev_b32_e32 v83, 1, v82
	v_xor_b32_e32 v83, v83, v82
	v_and_b32_e32 v83, 4, v83
	v_lshl_or_b32 v83, v83, 1, v83
	v_xor_b32_e32 v82, v82, v83
	v_mul_lo_u32 v82, v82, s22
	v_or3_b32 v82, v162, v82, v137
	v_ashrrev_i32_e32 v83, 31, v82
	v_lshlrev_b64 v[152:153], 1, v[82:83]
	v_add_u32_e32 v82, s59, v163
	v_lshrrev_b32_e32 v83, 1, v82
	v_xor_b32_e32 v83, v83, v82
	v_and_b32_e32 v83, 4, v83
	v_lshl_or_b32 v83, v83, 1, v83
	v_xor_b32_e32 v82, v82, v83
	v_mul_lo_u32 v82, v82, s22
	v_or3_b32 v82, v162, v82, v137
	s_waitcnt vmcnt(0)
	v_ashrrev_i32_e32 v83, 31, v82
	s_add_u32 s0, s90, s58
	v_lshlrev_b64 v[154:155], 1, v[82:83]
	v_lshl_add_u64 v[150:151], s[52:53], 0, v[150:151]
	s_addc_u32 s1, s91, s25
	v_or_b32_e32 v152, s24, v152
	v_or_b32_e32 v154, s24, v154
	s_mov_b32 s52, 4
	s_waitcnt vmcnt(0)
	s_barrier
	v_exp_f32_e32 v220, v66
	v_exp_f32_e32 v221, v67
	v_exp_f32_e32 v222, v68
	v_exp_f32_e32 v223, v69
	v_exp_f32_e32 v224, v70
	v_exp_f32_e32 v225, v71
	v_exp_f32_e32 v226, v72
	v_exp_f32_e32 v227, v73
	v_exp_f32_e32 v228, v74
	v_exp_f32_e32 v229, v75
	v_exp_f32_e32 v230, v76
	v_exp_f32_e32 v231, v77
	v_exp_f32_e32 v232, v78
	v_exp_f32_e32 v233, v79
	v_exp_f32_e32 v234, v80
	v_exp_f32_e32 v235, v81
	s_branch .LBB0_2320
.LBB0_2319:
	s_mov_b32 m0, s56
	v_lshl_add_u64 v[68:69], v[156:157], 0, s[44:45]
	global_load_lds_dwordx4 v[68:69], off
	v_lshl_add_u64 v[68:69], v[158:159], 0, s[44:45]
	s_mov_b32 m0, s57
	global_load_lds_dwordx4 v[68:69], off
	ds_read_b128 v[68:71], v172 offset:40960
	ds_read_b128 v[72:75], v172 offset:45056
	ds_read_b128 v[156:159], v173 offset:40960
	ds_read_b128 v[176:179], v173 offset:45056
	ds_read_b128 v[180:183], v174 offset:40960
	ds_read_b128 v[184:187], v174 offset:45056
	ds_read_b128 v[188:191], v175 offset:40960
	ds_read_b128 v[192:195], v175 offset:45056
	v_add_f32_e32 v66, v66, v67
	v_add_f32_e32 v135, v135, v66
	s_add_i32 s52, s52, 2
	s_waitcnt lgkmcnt(0)
	v_mfma_f32_32x32x16_bf16 v[98:113], v[68:71], v[114:117], 0
	v_mfma_f32_32x32x16_bf16 v[66:81], v[72:75], v[114:117], 0
	v_mfma_f32_32x32x16_bf16 v[66:81], v[176:179], v[118:121], v[66:81]
	v_mfma_f32_32x32x16_bf16 v[98:113], v[156:159], v[118:121], v[98:113]
	v_add_f32_e32 v82, v236, v237
	v_add_f32_e32 v83, v220, v221
	v_mfma_f32_32x32x16_bf16 v[66:81], v[184:187], v[122:125], v[66:81]
	v_add_f32_e32 v82, v82, v238
	v_add_f32_e32 v83, v83, v222
	v_cvt_pk_bf16_f32 v84, v240, v241
	v_add_f32_e32 v82, v82, v239
	v_add_f32_e32 v83, v83, v223
	v_cvt_pk_bf16_f32 v85, v244, v245
	v_add_f32_e32 v82, v82, v240
	v_add_f32_e32 v83, v83, v224
	v_mfma_f32_32x32x16_bf16 v[98:113], v[180:183], v[122:125], v[98:113]
	v_add_f32_e32 v82, v82, v241
	v_add_f32_e32 v83, v83, v225
	v_add_f32_e32 v82, v82, v244
	v_add_f32_e32 v83, v83, v226
	v_add_f32_e32 v82, v82, v245
	v_add_f32_e32 v83, v83, v227
	v_add_f32_e32 v82, v82, v246
	v_add_f32_e32 v83, v83, v228
	v_add_f32_e32 v82, v82, v247
	v_add_f32_e32 v83, v83, v229
	v_add_f32_e32 v82, v82, v248
	v_add_f32_e32 v83, v83, v230
	v_add_f32_e32 v82, v82, v249
	v_add_f32_e32 v83, v83, v231
	v_add_f32_e32 v82, v82, v250
	v_add_f32_e32 v83, v83, v232
	v_add_f32_e32 v82, v82, v251
	v_add_f32_e32 v83, v83, v233
	v_add_f32_e32 v82, v82, v252
	v_add_f32_e32 v83, v83, v234
	v_add_f32_e32 v82, v82, v253
	v_add_f32_e32 v83, v83, v235
	v_add_f32_e32 v82, v82, v83
	v_mov_b32_e32 v83, v82
	s_nop 1
	v_permlane32_swap_b32_e32 v82, v83
	v_add_f32_e32 v82, v82, v83
	v_add_f32_e32 v135, v135, v82
	v_cvt_pk_bf16_f32 v82, v236, v237
	v_cvt_pk_bf16_f32 v83, v238, v239
	v_mfma_f32_32x32x16_bf16 v[66:81], v[192:195], v[126:129], v[66:81]
	v_cvt_pk_bf16_f32 v86, v246, v247
	v_cvt_pk_bf16_f32 v87, v248, v249
	v_cvt_pk_bf16_f32 v88, v250, v251
	v_cvt_pk_bf16_f32 v89, v252, v253
	v_cvt_pk_bf16_f32 v90, v220, v221
	v_cvt_pk_bf16_f32 v91, v222, v223
	v_cvt_pk_bf16_f32 v92, v224, v225
	v_cvt_pk_bf16_f32 v93, v226, v227
	v_cvt_pk_bf16_f32 v94, v228, v229
	v_cvt_pk_bf16_f32 v95, v230, v231
	v_cvt_pk_bf16_f32 v96, v232, v233
	v_cvt_pk_bf16_f32 v97, v234, v235
	v_mfma_f32_32x32x16_bf16 v[98:113], v[188:191], v[126:129], v[98:113]
	ds_read_b64_tr_b16 v[156:157], v168 offset:0
	ds_read_b64_tr_b16 v[158:159], v168 offset:0x800
	ds_read_b64_tr_b16 v[176:177], v168 offset:0x1000
	ds_read_b64_tr_b16 v[178:179], v168 offset:0x1800
	ds_read_b64_tr_b16 v[180:181], v168 offset:0x2000
	ds_read_b64_tr_b16 v[182:183], v168 offset:0x2800
	ds_read_b64_tr_b16 v[184:185], v168 offset:0x3000
	ds_read_b64_tr_b16 v[186:187], v168 offset:0x3800
	ds_read_b64_tr_b16 v[188:189], v168 offset:0x200
	ds_read_b64_tr_b16 v[190:191], v168 offset:0xa00
	ds_read_b64_tr_b16 v[192:193], v168 offset:0x1200
	ds_read_b64_tr_b16 v[194:195], v168 offset:0x1a00
	ds_read_b64_tr_b16 v[196:197], v168 offset:0x2200
	ds_read_b64_tr_b16 v[198:199], v168 offset:0x2a00
	ds_read_b64_tr_b16 v[200:201], v168 offset:0x3200
	ds_read_b64_tr_b16 v[202:203], v168 offset:0x3a00
	s_waitcnt lgkmcnt(8)
	s_nop 0
	v_mfma_f32_32x32x16_bf16 v[2:17], v[82:85], v[156:159], v[2:17]
	v_exp_f32_e32 v220, v66
	s_nop 3
	v_exp_f32_e32 v139, v98
	v_exp_f32_e32 v141, v99
	v_exp_f32_e32 v143, v100
	v_exp_f32_e32 v145, v101
	v_mfma_f32_32x32x16_bf16 v[2:17], v[86:89], v[176:179], v[2:17]
	v_exp_f32_e32 v221, v67
	v_mfma_f32_32x32x16_bf16 v[2:17], v[90:93], v[180:183], v[2:17]
	v_exp_f32_e32 v222, v68
	v_mfma_f32_32x32x16_bf16 v[2:17], v[94:97], v[184:187], v[2:17]
	v_exp_f32_e32 v223, v69
	ds_read_b64_tr_b16 v[98:99], v168 offset:0x400
	ds_read_b64_tr_b16 v[100:101], v168 offset:0xc00
	ds_read_b64_tr_b16 v[156:157], v168 offset:0x1400
	ds_read_b64_tr_b16 v[158:159], v168 offset:0x1c00
	ds_read_b64_tr_b16 v[178:179], v168 offset:0x2400
	ds_read_b64_tr_b16 v[180:181], v168 offset:0x2c00
	ds_read_b64_tr_b16 v[182:183], v168 offset:0x3400
	ds_read_b64_tr_b16 v[184:185], v168 offset:0x3c00
	s_waitcnt lgkmcnt(8)
	v_mfma_f32_32x32x16_bf16 v[18:33], v[82:85], v[188:191], v[18:33]
	v_exp_f32_e32 v224, v70
	v_exp_f32_e32 v147, v102
	v_exp_f32_e32 v149, v103
	v_exp_f32_e32 v176, v104
	v_exp_f32_e32 v177, v105
	v_mfma_f32_32x32x16_bf16 v[18:33], v[86:89], v[192:195], v[18:33]
	v_exp_f32_e32 v225, v71
	v_mfma_f32_32x32x16_bf16 v[18:33], v[90:93], v[196:199], v[18:33]
	v_exp_f32_e32 v226, v72
	v_mfma_f32_32x32x16_bf16 v[18:33], v[94:97], v[200:203], v[18:33]
	v_exp_f32_e32 v227, v73
	ds_read_b64_tr_b16 v[102:103], v168 offset:0x600
	ds_read_b64_tr_b16 v[104:105], v168 offset:0xe00
	ds_read_b64_tr_b16 v[186:187], v168 offset:0x1600
	ds_read_b64_tr_b16 v[188:189], v168 offset:0x1e00
	ds_read_b64_tr_b16 v[190:191], v168 offset:0x2600
	ds_read_b64_tr_b16 v[192:193], v168 offset:0x2e00
	ds_read_b64_tr_b16 v[194:195], v168 offset:0x3600
	ds_read_b64_tr_b16 v[196:197], v168 offset:0x3e00
	s_waitcnt lgkmcnt(8)
	v_mfma_f32_32x32x16_bf16 v[34:49], v[82:85], v[98:101], v[34:49]
	v_exp_f32_e32 v228, v74
	v_mfma_f32_32x32x16_bf16 v[34:49], v[86:89], v[156:159], v[34:49]
	v_exp_f32_e32 v229, v75
	v_mfma_f32_32x32x16_bf16 v[34:49], v[90:93], v[178:181], v[34:49]
	v_exp_f32_e32 v230, v76
	v_exp_f32_e32 v178, v106
	v_exp_f32_e32 v179, v107
	v_exp_f32_e32 v180, v108
	v_exp_f32_e32 v181, v109
	v_mfma_f32_32x32x16_bf16 v[34:49], v[94:97], v[182:185], v[34:49]
	v_exp_f32_e32 v231, v77
	s_waitcnt lgkmcnt(0)
	v_mfma_f32_32x32x16_bf16 v[50:65], v[82:85], v[102:105], v[50:65]
	v_exp_f32_e32 v232, v78
	v_exp_f32_e32 v182, v110
	v_exp_f32_e32 v183, v111
	v_exp_f32_e32 v184, v112
	v_exp_f32_e32 v185, v113
	v_mfma_f32_32x32x16_bf16 v[50:65], v[86:89], v[186:189], v[50:65]
	v_exp_f32_e32 v233, v79
	v_mfma_f32_32x32x16_bf16 v[50:65], v[90:93], v[190:193], v[50:65]
	v_exp_f32_e32 v234, v80
	v_mfma_f32_32x32x16_bf16 v[50:65], v[94:97], v[194:197], v[50:65]
	v_exp_f32_e32 v235, v81
	s_waitcnt vmcnt(0)
	s_add_u32 s0, s0, 0x180000
	s_addc_u32 s1, s1, 0
	s_and_b64 vcc, exec, s[24:25]
	s_waitcnt vmcnt(0)
	s_barrier
	s_cbranch_vccnz .LBB0_2322
